# attention: Q-load wait ladders removed from unit prologues (Q latency overlaps K/V DMA issue); diff-attention unit epilogue: 15 serialized subln gain loads hoisted and counted-waited
# baseline (speedup 1.0000x reference)
; __device__ __forceinline__ float bf_lo(unsigned w) { return __uint_as_float(w << 16); }
; __device__ __forceinline__ float bf_hi(unsigned w) { return __uint_as_float(w & 0xffff0000u); }
; #define GAS __attribute__((address_space(1)))
; __device__ __forceinline__ float xhalf_sum(float v) { auto rr = __builtin_amdgcn_permlane32_swap(__float_as_uint(v), __float_as_uint(v), false, false); return __uint_as_float(rr[0]) + __uint_as_float(rr[1]); }
; __device__ __forceinline__ void attention_phase(const KP& p, LAS unsigned char* lds, unsigned char* ws, int rep) {
;     ...
;             f32x16 oB[4]; float lB;
;             attn_pass<64, 128, false>(lds, Qd + (rb + q0w + r32) * 512 + (2 * h + 1) * 64, Kd + rb * 512 + (2 * h + 1) * 64, 512, nullptr, Vt, NT, q0w, oB, lB, tid);
;             const float ib = lam / lB;
;             float ss = 0.f;
; #pragma unroll
;             for (int d = 0; d < 4; ++d)
; #pragma unroll
;                 for (int g = 0; g < 4; ++g) {
;                     const u32x2 a = *(const GAS u32x2*)(yo + 32 * d + 8 * g + 4 * hi);
;                     const float v0 = bf_lo(a.x) - oB[d][4 * g] * ib, v1 = bf_hi(a.x) - oB[d][4 * g + 1] * ib, v2 = bf_lo(a.y) - oB[d][4 * g + 2] * ib, v3 = bf_hi(a.y) - oB[d][4 * g + 3] * ib;
;                     oB[d][4 * g] = v0; oB[d][4 * g + 1] = v1; oB[d][4 * g + 2] = v2; oB[d][4 * g + 3] = v3;
;                     ss += (v0 * v0 + v1 * v1) + (v2 * v2 + v3 * v3);
;                 }
;             ss = xhalf_sum(ss);
.LBB0_44:
	s_or_b64 exec, exec, s[6:7]
	s_waitcnt lgkmcnt(0)
	s_barrier
	global_load_dwordx2 v[58:59], v[194:195], off offset:1024
	global_load_dwordx2 v[60:61], v[194:195], off offset:1040
	global_load_dwordx2 v[62:63], v[194:195], off offset:1056
	global_load_dwordx2 v[64:65], v[194:195], off offset:1072
	global_load_dwordx2 v[98:99], v[194:195], off offset:1088
	global_load_dwordx2 v[100:101], v[194:195], off offset:1104
	global_load_dwordx2 v[102:103], v[194:195], off offset:1120
	global_load_dwordx2 v[104:105], v[194:195], off offset:1136
	global_load_dwordx2 v[106:107], v[194:195], off offset:1152
	global_load_dwordx2 v[94:95], v[194:195], off offset:1168
	global_load_dwordx2 v[92:93], v[194:195], off offset:1184
	global_load_dwordx2 v[90:91], v[194:195], off offset:1200
	global_load_dwordx2 v[88:89], v[194:195], off offset:1216
	global_load_dwordx2 v[82:83], v[194:195], off offset:1232
	global_load_dwordx2 v[56:57], v[194:195], off offset:1248
	global_load_dwordx2 v[54:55], v[194:195], off offset:1264
	v_mov_b32_e32 v50, v206
	s_nop 1
	v_permlane32_swap_b32_e32 v206, v50
	v_lshlrev_b32_e32 v96, 2, v0
	v_add_f32_e32 v0, v206, v50
	v_div_scale_f32 v84, s[6:7], v0, v0, v237
	v_rcp_f32_e32 v85, v84
	v_div_scale_f32 v86, vcc, v237, v0, v237
	global_load_dwordx4 v[50:53], v96, s[76:77]
	v_fma_f32 v87, -v84, v85, 1.0
	v_fmac_f32_e32 v85, v87, v85
	v_mul_f32_e32 v87, v86, v85
	v_fma_f32 v97, -v84, v87, v86
	v_fmac_f32_e32 v87, v97, v85
	v_fma_f32 v84, -v84, v87, v86
	v_div_fmas_f32 v84, v84, v85, v87
	v_div_fixup_f32 v0, v84, v0, v237
	s_waitcnt vmcnt(16)
	v_lshlrev_b32_e32 v84, 16, v59
	v_and_b32_e32 v85, 0xffff0000, v59
	v_lshlrev_b32_e32 v86, 16, v58
	v_and_b32_e32 v87, 0xffff0000, v58
	s_waitcnt vmcnt(15)
	v_lshlrev_b32_e32 v58, 16, v61
	v_and_b32_e32 v59, 0xffff0000, v61
	v_lshlrev_b32_e32 v108, 16, v60
	v_and_b32_e32 v109, 0xffff0000, v60
	s_waitcnt vmcnt(14)
	v_lshlrev_b32_e32 v60, 16, v63
	v_and_b32_e32 v61, 0xffff0000, v63
	v_pk_fma_f32 v[84:85], v[68:69], v[0:1], v[84:85] op_sel_hi:[1,0,1] neg_lo:[1,0,0] neg_hi:[1,0,0]
	v_pk_fma_f32 v[86:87], v[66:67], v[0:1], v[86:87] op_sel_hi:[1,0,1] neg_lo:[1,0,0] neg_hi:[1,0,0]
	v_pk_fma_f32 v[66:67], v[72:73], v[0:1], v[58:59] op_sel_hi:[1,0,1] neg_lo:[1,0,0] neg_hi:[1,0,0]
	v_pk_fma_f32 v[68:69], v[70:71], v[0:1], v[108:109] op_sel_hi:[1,0,1] neg_lo:[1,0,0] neg_hi:[1,0,0]
	v_lshlrev_b32_e32 v110, 16, v62
	v_and_b32_e32 v111, 0xffff0000, v62
	v_pk_fma_f32 v[62:63], v[76:77], v[0:1], v[60:61] op_sel_hi:[1,0,1] neg_lo:[1,0,0] neg_hi:[1,0,0]
	v_mov_b32_e32 v72, v87
	v_mov_b32_e32 v73, v85
	v_mov_b32_e32 v76, v69
	v_mov_b32_e32 v77, v67
	s_waitcnt vmcnt(13)
	v_lshlrev_b32_e32 v112, 16, v65
	v_and_b32_e32 v113, 0xffff0000, v65
	v_lshlrev_b32_e32 v114, 16, v64
	v_and_b32_e32 v115, 0xffff0000, v64
	v_pk_fma_f32 v[64:65], v[74:75], v[0:1], v[110:111] op_sel_hi:[1,0,1] neg_lo:[1,0,0] neg_hi:[1,0,0]
	v_mov_b32_e32 v70, v86
	v_mov_b32_e32 v71, v84
	v_mov_b32_e32 v74, v68
	v_mov_b32_e32 v75, v66
	v_pk_mul_f32 v[72:73], v[72:73], v[72:73]
	v_pk_mul_f32 v[76:77], v[76:77], v[76:77]
	v_pk_fma_f32 v[58:59], v[80:81], v[0:1], v[112:113] op_sel_hi:[1,0,1] neg_lo:[1,0,0] neg_hi:[1,0,0]
	v_pk_fma_f32 v[60:61], v[78:79], v[0:1], v[114:115] op_sel_hi:[1,0,1] neg_lo:[1,0,0] neg_hi:[1,0,0]
	v_mul_f32_e32 v78, v63, v63
	v_mul_f32_e32 v80, v65, v65
	v_pk_fma_f32 v[70:71], v[70:71], v[70:71], v[72:73]
	v_pk_fma_f32 v[72:73], v[74:75], v[74:75], v[76:77]
	v_pk_mul_f32 v[108:109], v[58:59], v[58:59]
	v_pk_mul_f32 v[110:111], v[60:61], v[60:61]
	v_pk_fma_f32 v[78:79], v[62:63], v[62:63], v[78:79] op_sel_hi:[1,1,0]
	v_pk_fma_f32 v[80:81], v[64:65], v[64:65], v[80:81] op_sel_hi:[1,1,0]
	v_pk_add_f32 v[70:71], v[70:71], v[70:71] op_sel:[0,1] op_sel_hi:[1,0]
	v_pk_add_f32 v[72:73], v[72:73], v[72:73] op_sel:[0,1] op_sel_hi:[1,0]
	v_mov_b32_e32 v81, v108
	v_mov_b32_e32 v79, v109
	v_mov_b32_e32 v71, v110
	v_mov_b32_e32 v73, v111
	v_pk_add_f32 v[74:75], v[80:81], v[78:79]
	v_pk_add_f32 v[70:71], v[70:71], v[72:73]
	s_waitcnt vmcnt(10)
	v_lshlrev_b32_e32 v80, 16, v102
	v_pk_add_f32 v[70:71], v[70:71], v[74:75]
	v_and_b32_e32 v81, 0xffff0000, v102
	v_pk_add_f32 v[72:73], v[70:71], v[70:71] op_sel:[0,1] op_sel_hi:[1,0]
	v_lshlrev_b32_e32 v70, 16, v99
	v_and_b32_e32 v71, 0xffff0000, v99
	v_pk_fma_f32 v[36:37], v[36:37], v[0:1], v[70:71] op_sel_hi:[1,0,1] neg_lo:[1,0,0] neg_hi:[1,0,0]
	v_lshlrev_b32_e32 v70, 16, v98
	v_and_b32_e32 v71, 0xffff0000, v98
	v_pk_fma_f32 v[70:71], v[34:35], v[0:1], v[70:71] op_sel_hi:[1,0,1] neg_lo:[1,0,0] neg_hi:[1,0,0]
	v_mov_b32_e32 v75, v37
	v_mov_b32_e32 v74, v71
	v_mov_b32_e32 v34, v70
	v_mov_b32_e32 v35, v36
	v_pk_mul_f32 v[74:75], v[74:75], v[74:75]
	v_pk_fma_f32 v[42:43], v[42:43], v[0:1], v[80:81] op_sel_hi:[1,0,1] neg_lo:[1,0,0] neg_hi:[1,0,0]
	v_pk_fma_f32 v[34:35], v[34:35], v[34:35], v[74:75]
	v_pk_mul_f32 v[80:81], v[42:43], v[42:43]
	v_pk_add_f32 v[74:75], v[34:35], v[34:35] op_sel:[0,1] op_sel_hi:[1,0]
	v_lshlrev_b32_e32 v34, 16, v101
	v_and_b32_e32 v35, 0xffff0000, v101
	v_pk_fma_f32 v[34:35], v[40:41], v[0:1], v[34:35] op_sel_hi:[1,0,1] neg_lo:[1,0,0] neg_hi:[1,0,0]
	v_mov_b32_e32 v73, v80
	v_mul_f32_e32 v40, v35, v35
	v_pk_fma_f32 v[76:77], v[34:35], v[34:35], v[40:41] op_sel_hi:[1,1,0]
	v_lshlrev_b32_e32 v40, 16, v100
	v_and_b32_e32 v41, 0xffff0000, v100
	v_pk_fma_f32 v[40:41], v[38:39], v[0:1], v[40:41] op_sel_hi:[1,0,1] neg_lo:[1,0,0] neg_hi:[1,0,0]
	v_mov_b32_e32 v75, v81
	v_mul_f32_e32 v38, v41, v41
	v_pk_fma_f32 v[78:79], v[40:41], v[40:41], v[38:39] op_sel_hi:[1,1,0]
	v_lshlrev_b32_e32 v38, 16, v103
	v_and_b32_e32 v39, 0xffff0000, v103
	v_pk_fma_f32 v[38:39], v[44:45], v[0:1], v[38:39] op_sel_hi:[1,0,1] neg_lo:[1,0,0] neg_hi:[1,0,0]
	v_pk_add_f32 v[72:73], v[72:73], v[74:75]
	v_pk_mul_f32 v[44:45], v[38:39], v[38:39]
	s_waitcnt vmcnt(7)
; __device__ __forceinline__ unsigned cvtpk(float lo, float hi) { const f32x2 v = {lo, hi}; const bf16x2_t b = __builtin_convertvector(v, bf16x2_t); return __builtin_bit_cast(unsigned, b); }
; __device__ __forceinline__ float bf_lo(unsigned w) { return __uint_as_float(w << 16); }
; __device__ __forceinline__ float bf_hi(unsigned w) { return __uint_as_float(w & 0xffff0000u); }
; #define GAS __attribute__((address_space(1)))
; __device__ __forceinline__ float xhalf_sum(float v) { auto rr = __builtin_amdgcn_permlane32_swap(__float_as_uint(v), __float_as_uint(v), false, false); return __uint_as_float(rr[0]) + __uint_as_float(rr[1]); }
; __device__ __forceinline__ void attention_phase(const KP& p, LAS unsigned char* lds, unsigned char* ws, int rep) {
;     ...
;             for (int d = 0; d < 4; ++d)
; #pragma unroll
;                 for (int g = 0; g < 4; ++g) {
;                     const u32x2 a = *(const GAS u32x2*)(yo + 32 * d + 8 * g + 4 * hi);
;                     const float v0 = bf_lo(a.x) - oB[d][4 * g] * ib, v1 = bf_hi(a.x) - oB[d][4 * g + 1] * ib, v2 = bf_lo(a.y) - oB[d][4 * g + 2] * ib, v3 = bf_hi(a.y) - oB[d][4 * g + 3] * ib;
;                     oB[d][4 * g] = v0; oB[d][4 * g + 1] = v1; oB[d][4 * g + 2] = v2; oB[d][4 * g + 3] = v3;
;                     ss += (v0 * v0 + v1 * v1) + (v2 * v2 + v3 * v3);
;                 }
;             ss = xhalf_sum(ss);
;             const float rn = rsqrtf(ss * (1.0f / 128.0f) + EPS) * p.one_m_lam;
; #pragma unroll
;             for (int d = 0; d < 4; ++d)
; #pragma unroll
;                 for (int g = 0; g < 4; ++g) {
;                     const int dd = 32 * d + 8 * g + 4 * hi;
;                     const f32x4 sg = *(const f32x4*)(p.subln + dd);
;                     u32x2 wv; wv.x = cvtpk(oB[d][4 * g] * rn * sg[0], oB[d][4 * g + 1] * rn * sg[1]); wv.y = cvtpk(oB[d][4 * g + 2] * rn * sg[2], oB[d][4 * g + 3] * rn * sg[3]);
	v_lshlrev_b32_e32 v80, 16, v94
	v_mov_b32_e32 v79, v44
	v_mov_b32_e32 v77, v45
	v_pk_add_f32 v[44:45], v[78:79], v[76:77]
	v_and_b32_e32 v81, 0xffff0000, v94
	v_pk_add_f32 v[44:45], v[72:73], v[44:45]
	v_pk_fma_f32 v[22:23], v[22:23], v[0:1], v[80:81] op_sel_hi:[1,0,1] neg_lo:[1,0,0] neg_hi:[1,0,0]
	v_pk_add_f32 v[72:73], v[44:45], v[44:45] op_sel:[0,1] op_sel_hi:[1,0]
	v_lshlrev_b32_e32 v44, 16, v105
	v_and_b32_e32 v45, 0xffff0000, v105
	v_pk_fma_f32 v[44:45], v[48:49], v[0:1], v[44:45] op_sel_hi:[1,0,1] neg_lo:[1,0,0] neg_hi:[1,0,0]
	v_lshlrev_b32_e32 v48, 16, v104
	v_and_b32_e32 v49, 0xffff0000, v104
	v_pk_fma_f32 v[46:47], v[46:47], v[0:1], v[48:49] op_sel_hi:[1,0,1] neg_lo:[1,0,0] neg_hi:[1,0,0]
	v_mov_b32_e32 v75, v45
	v_mov_b32_e32 v74, v47
	v_mov_b32_e32 v48, v46
	v_mov_b32_e32 v49, v44
	v_pk_mul_f32 v[74:75], v[74:75], v[74:75]
	v_pk_mul_f32 v[80:81], v[22:23], v[22:23]
	v_pk_fma_f32 v[48:49], v[48:49], v[48:49], v[74:75]
	v_mov_b32_e32 v73, v80
	v_pk_add_f32 v[74:75], v[48:49], v[48:49] op_sel:[0,1] op_sel_hi:[1,0]
	v_lshlrev_b32_e32 v48, 16, v107
	v_and_b32_e32 v49, 0xffff0000, v107
	v_pk_fma_f32 v[20:21], v[20:21], v[0:1], v[48:49] op_sel_hi:[1,0,1] neg_lo:[1,0,0] neg_hi:[1,0,0]
	v_mov_b32_e32 v75, v81
	v_mul_f32_e32 v48, v21, v21
	v_pk_fma_f32 v[76:77], v[20:21], v[20:21], v[48:49] op_sel_hi:[1,1,0]
	v_lshlrev_b32_e32 v48, 16, v106
	v_and_b32_e32 v49, 0xffff0000, v106
	v_pk_fma_f32 v[48:49], v[18:19], v[0:1], v[48:49] op_sel_hi:[1,0,1] neg_lo:[1,0,0] neg_hi:[1,0,0]
	v_pk_add_f32 v[72:73], v[72:73], v[74:75]
	v_mul_f32_e32 v18, v49, v49
	v_pk_fma_f32 v[78:79], v[48:49], v[48:49], v[18:19] op_sel_hi:[1,1,0]
	v_lshlrev_b32_e32 v18, 16, v95
	v_and_b32_e32 v19, 0xffff0000, v95
	v_pk_fma_f32 v[18:19], v[24:25], v[0:1], v[18:19] op_sel_hi:[1,0,1] neg_lo:[1,0,0] neg_hi:[1,0,0]
	s_waitcnt vmcnt(4)
	v_lshlrev_b32_e32 v80, 16, v88
	v_pk_mul_f32 v[24:25], v[18:19], v[18:19]
	v_and_b32_e32 v81, 0xffff0000, v88
	v_mov_b32_e32 v79, v24
	v_mov_b32_e32 v77, v25
	v_pk_add_f32 v[24:25], v[78:79], v[76:77]
	v_lshlrev_b32_e32 v76, 16, v90
	v_pk_add_f32 v[24:25], v[72:73], v[24:25]
	v_and_b32_e32 v77, 0xffff0000, v90
	v_pk_add_f32 v[72:73], v[24:25], v[24:25] op_sel:[0,1] op_sel_hi:[1,0]
	v_lshlrev_b32_e32 v24, 16, v93
	v_and_b32_e32 v25, 0xffff0000, v93
	v_pk_fma_f32 v[24:25], v[28:29], v[0:1], v[24:25] op_sel_hi:[1,0,1] neg_lo:[1,0,0] neg_hi:[1,0,0]
	v_lshlrev_b32_e32 v28, 16, v92
	v_and_b32_e32 v29, 0xffff0000, v92
	v_pk_fma_f32 v[28:29], v[26:27], v[0:1], v[28:29] op_sel_hi:[1,0,1] neg_lo:[1,0,0] neg_hi:[1,0,0]
	v_mov_b32_e32 v75, v25
	v_mov_b32_e32 v74, v29
	v_mov_b32_e32 v26, v28
	v_mov_b32_e32 v27, v24
	v_pk_mul_f32 v[74:75], v[74:75], v[74:75]
	v_pk_fma_f32 v[30:31], v[30:31], v[0:1], v[76:77] op_sel_hi:[1,0,1] neg_lo:[1,0,0] neg_hi:[1,0,0]
	v_pk_fma_f32 v[26:27], v[26:27], v[26:27], v[74:75]
	v_lshlrev_b32_e32 v78, 16, v89
	v_pk_add_f32 v[74:75], v[26:27], v[26:27] op_sel:[0,1] op_sel_hi:[1,0]
	v_lshlrev_b32_e32 v26, 16, v91
	v_and_b32_e32 v27, 0xffff0000, v91
	v_pk_fma_f32 v[26:27], v[32:33], v[0:1], v[26:27] op_sel_hi:[1,0,1] neg_lo:[1,0,0] neg_hi:[1,0,0]
	v_and_b32_e32 v79, 0xffff0000, v89
	v_mul_f32_e32 v32, v27, v27
	v_mul_f32_e32 v76, v31, v31
	v_pk_fma_f32 v[4:5], v[4:5], v[0:1], v[78:79] op_sel_hi:[1,0,1] neg_lo:[1,0,0] neg_hi:[1,0,0]
	v_pk_fma_f32 v[2:3], v[2:3], v[0:1], v[80:81] op_sel_hi:[1,0,1] neg_lo:[1,0,0] neg_hi:[1,0,0]
	v_pk_fma_f32 v[32:33], v[26:27], v[26:27], v[32:33] op_sel_hi:[1,1,0]
	v_pk_fma_f32 v[76:77], v[30:31], v[30:31], v[76:77] op_sel_hi:[1,1,0]
	v_pk_mul_f32 v[78:79], v[4:5], v[4:5]
	v_pk_mul_f32 v[80:81], v[2:3], v[2:3]
	v_mov_b32_e32 v77, v78
	v_mov_b32_e32 v33, v79
	v_mov_b32_e32 v73, v80
	v_mov_b32_e32 v75, v81
	v_pk_add_f32 v[32:33], v[76:77], v[32:33]
	v_pk_add_f32 v[72:73], v[72:73], v[74:75]
	s_waitcnt vmcnt(2)
	v_lshlrev_b32_e32 v76, 16, v56
	v_pk_add_f32 v[32:33], v[72:73], v[32:33]
	v_lshlrev_b32_e32 v72, 16, v83
	v_and_b32_e32 v73, 0xffff0000, v83
	v_pk_fma_f32 v[8:9], v[8:9], v[0:1], v[72:73] op_sel_hi:[1,0,1] neg_lo:[1,0,0] neg_hi:[1,0,0]
	v_lshlrev_b32_e32 v72, 16, v82
	v_and_b32_e32 v73, 0xffff0000, v82
	v_pk_fma_f32 v[6:7], v[6:7], v[0:1], v[72:73] op_sel_hi:[1,0,1] neg_lo:[1,0,0] neg_hi:[1,0,0]
	v_mov_b32_e32 v75, v9
	v_mov_b32_e32 v74, v7
	v_mov_b32_e32 v72, v6
	v_mov_b32_e32 v73, v8
	v_pk_mul_f32 v[74:75], v[74:75], v[74:75]
	v_and_b32_e32 v77, 0xffff0000, v56
	v_pk_fma_f32 v[72:73], v[72:73], v[72:73], v[74:75]
	v_lshlrev_b32_e32 v74, 16, v57
	v_and_b32_e32 v75, 0xffff0000, v57
	v_pk_fma_f32 v[74:75], v[12:13], v[0:1], v[74:75] op_sel_hi:[1,0,1] neg_lo:[1,0,0] neg_hi:[1,0,0]
	v_pk_fma_f32 v[56:57], v[10:11], v[0:1], v[76:77] op_sel_hi:[1,0,1] neg_lo:[1,0,0] neg_hi:[1,0,0]
	s_waitcnt vmcnt(1)
	v_lshlrev_b32_e32 v76, 16, v55
	v_and_b32_e32 v77, 0xffff0000, v55
	v_lshlrev_b32_e32 v78, 16, v54
	v_and_b32_e32 v79, 0xffff0000, v54
	v_mul_f32_e32 v12, v75, v75
	v_mul_f32_e32 v10, v57, v57
	v_pk_fma_f32 v[16:17], v[16:17], v[0:1], v[76:77] op_sel_hi:[1,0,1] neg_lo:[1,0,0] neg_hi:[1,0,0]
	v_pk_fma_f32 v[14:15], v[14:15], v[0:1], v[78:79] op_sel_hi:[1,0,1] neg_lo:[1,0,0] neg_hi:[1,0,0]
	v_pk_add_f32 v[32:33], v[32:33], v[32:33] op_sel:[0,1] op_sel_hi:[1,0]
	v_pk_add_f32 v[72:73], v[72:73], v[72:73] op_sel:[0,1] op_sel_hi:[1,0]
	v_pk_fma_f32 v[12:13], v[74:75], v[74:75], v[12:13] op_sel_hi:[1,1,0]
	v_pk_fma_f32 v[10:11], v[56:57], v[56:57], v[10:11] op_sel_hi:[1,1,0]
	v_pk_mul_f32 v[76:77], v[16:17], v[16:17]
	v_pk_mul_f32 v[54:55], v[14:15], v[14:15]
	v_mov_b32_e32 v11, v76
	v_mov_b32_e32 v13, v77
	v_mov_b32_e32 v33, v54
	v_mov_b32_e32 v73, v55
	v_pk_add_f32 v[10:11], v[10:11], v[12:13]
	v_pk_add_f32 v[12:13], v[32:33], v[72:73]
	s_nop 0
	v_pk_add_f32 v[10:11], v[12:13], v[10:11]
	s_nop 0
	v_pk_add_f32 v[10:11], v[10:11], v[10:11] op_sel:[0,1] op_sel_hi:[1,0]
	s_nop 0
	v_mov_b32_e32 v0, v10
	s_nop 1
	v_permlane32_swap_b32_e32 v10, v0
	v_add_f32_e32 v0, v10, v0
	v_fmamk_f32 v0, v0, 0x3c000000, v217
	v_mul_f32_e32 v10, 0x4b800000, v0
	v_cmp_gt_f32_e32 vcc, s37, v0
	s_nop 1
	v_cndmask_b32_e32 v0, v0, v10, vcc
	v_rsq_f32_e32 v0, v0
	s_nop 0
	v_mul_f32_e32 v10, 0x45800000, v0
	v_cndmask_b32_e32 v0, v0, v10, vcc
	v_mul_f32_e32 v0, s87, v0
	v_pk_mul_f32 v[10:11], v[86:87], v[0:1] op_sel_hi:[1,0]
	v_pk_mul_f32 v[12:13], v[84:85], v[0:1] op_sel_hi:[1,0]
	s_waitcnt vmcnt(0)
; __device__ __forceinline__ unsigned cvtpk(float lo, float hi) { const f32x2 v = {lo, hi}; const bf16x2_t b = __builtin_convertvector(v, bf16x2_t); return __builtin_bit_cast(unsigned, b); }
; #define GAS __attribute__((address_space(1)))
; __device__ __forceinline__ void attention_phase(const KP& p, LAS unsigned char* lds, unsigned char* ws, int rep) {
;     ...
; #pragma unroll
;             for (int d = 0; d < 4; ++d)
; #pragma unroll
;                 for (int g = 0; g < 4; ++g) {
;                     const int dd = 32 * d + 8 * g + 4 * hi;
;                     const f32x4 sg = *(const f32x4*)(p.subln + dd);
;                     u32x2 wv; wv.x = cvtpk(oB[d][4 * g] * rn * sg[0], oB[d][4 * g + 1] * rn * sg[1]); wv.y = cvtpk(oB[d][4 * g + 2] * rn * sg[2], oB[d][4 * g + 3] * rn * sg[3]);
;                     *(GAS u32x2*)(yo + dd) = wv;
;                 }
	v_pk_mul_f32 v[10:11], v[50:51], v[10:11]
	v_pk_mul_f32 v[12:13], v[52:53], v[12:13]
	v_cvt_pk_bf16_f32 v10, v10, v11
	v_cvt_pk_bf16_f32 v11, v12, v13
	global_store_dwordx2 v[194:195], v[10:11], off offset:1024
	global_load_dwordx4 v[120:123], v96, s[76:77] offset:32
	global_load_dwordx4 v[124:127], v96, s[76:77] offset:64
	global_load_dwordx4 v[128:131], v96, s[76:77] offset:96
	global_load_dwordx4 v[132:135], v96, s[76:77] offset:128
	global_load_dwordx4 v[136:139], v96, s[76:77] offset:160
	global_load_dwordx4 v[140:143], v96, s[76:77] offset:192
	global_load_dwordx4 v[144:147], v96, s[76:77] offset:224
	global_load_dwordx4 v[148:151], v96, s[76:77] offset:256
	global_load_dwordx4 v[152:155], v96, s[76:77] offset:288
	global_load_dwordx4 v[156:159], v96, s[76:77] offset:320
	global_load_dwordx4 v[160:163], v96, s[76:77] offset:352
	global_load_dwordx4 v[164:167], v96, s[76:77] offset:384
	global_load_dwordx4 v[168:171], v96, s[76:77] offset:416
	global_load_dwordx4 v[172:175], v96, s[76:77] offset:448
	global_load_dwordx4 v[176:179], v96, s[76:77] offset:480
	v_pk_mul_f32 v[32:33], v[68:69], v[0:1] op_sel_hi:[1,0]
	v_pk_mul_f32 v[50:51], v[62:63], v[0:1] op_sel_hi:[1,0]
	v_pk_mul_f32 v[36:37], v[36:37], v[0:1] op_sel_hi:[1,0]
	v_pk_mul_f32 v[34:35], v[34:35], v[0:1] op_sel_hi:[1,0]
	v_pk_mul_f32 v[20:21], v[20:21], v[0:1] op_sel_hi:[1,0]
	v_pk_mul_f32 v[18:19], v[18:19], v[0:1] op_sel_hi:[1,0]
	v_pk_mul_f32 v[2:3], v[2:3], v[0:1] op_sel_hi:[1,0]
	v_pk_mul_f32 v[4:5], v[4:5], v[0:1] op_sel_hi:[1,0]
	v_pk_mul_f32 v[6:7], v[6:7], v[0:1] op_sel_hi:[1,0]
	v_pk_mul_f32 v[8:9], v[8:9], v[0:1] op_sel_hi:[1,0]
	s_waitcnt vmcnt(14)
	v_pk_mul_f32 v[120:121], v[120:121], v[32:33]
	v_pk_mul_f32 v[32:33], v[66:67], v[0:1] op_sel_hi:[1,0]
	v_cvt_pk_bf16_f32 v120, v120, v121
	v_pk_mul_f32 v[122:123], v[122:123], v[32:33]
	v_pk_mul_f32 v[32:33], v[64:65], v[0:1] op_sel_hi:[1,0]
	v_cvt_pk_bf16_f32 v121, v122, v123
	global_store_dwordx2 v[194:195], v[120:121], off offset:1040
	s_waitcnt vmcnt(14)
	v_pk_mul_f32 v[124:125], v[124:125], v[32:33]
	v_pk_mul_f32 v[126:127], v[126:127], v[50:51]
	v_cvt_pk_bf16_f32 v124, v124, v125
	v_cvt_pk_bf16_f32 v125, v126, v127
	global_store_dwordx2 v[194:195], v[124:125], off offset:1056
	v_pk_mul_f32 v[32:33], v[60:61], v[0:1] op_sel_hi:[1,0]
	v_pk_mul_f32 v[50:51], v[58:59], v[0:1] op_sel_hi:[1,0]
	s_waitcnt vmcnt(14)
	v_pk_mul_f32 v[128:129], v[128:129], v[32:33]
	v_pk_mul_f32 v[130:131], v[130:131], v[50:51]
	v_cvt_pk_bf16_f32 v128, v128, v129
	v_cvt_pk_bf16_f32 v129, v130, v131
	global_store_dwordx2 v[194:195], v[128:129], off offset:1072
	v_pk_mul_f32 v[32:33], v[70:71], v[0:1] op_sel_hi:[1,0]
	s_waitcnt vmcnt(14)
	v_pk_mul_f32 v[134:135], v[134:135], v[36:37]
	v_pk_mul_f32 v[132:133], v[132:133], v[32:33]
	v_pk_mul_f32 v[32:33], v[40:41], v[0:1] op_sel_hi:[1,0]
	v_cvt_pk_bf16_f32 v132, v132, v133
	v_cvt_pk_bf16_f32 v133, v134, v135
	global_store_dwordx2 v[194:195], v[132:133], off offset:1088
	s_waitcnt vmcnt(14)
	v_pk_mul_f32 v[136:137], v[32:33], v[136:137]
	v_pk_mul_f32 v[138:139], v[34:35], v[138:139]
	v_cvt_pk_bf16_f32 v136, v136, v137
	v_cvt_pk_bf16_f32 v137, v138, v139
	global_store_dwordx2 v[194:195], v[136:137], off offset:1104
	v_pk_mul_f32 v[32:33], v[42:43], v[0:1] op_sel_hi:[1,0]
	v_pk_mul_f32 v[34:35], v[38:39], v[0:1] op_sel_hi:[1,0]
	s_waitcnt vmcnt(14)
	v_pk_mul_f32 v[140:141], v[32:33], v[140:141]
	v_pk_mul_f32 v[142:143], v[34:35], v[142:143]
	v_cvt_pk_bf16_f32 v140, v140, v141
	v_cvt_pk_bf16_f32 v141, v142, v143
	global_store_dwordx2 v[194:195], v[140:141], off offset:1120
	v_pk_mul_f32 v[32:33], v[46:47], v[0:1] op_sel_hi:[1,0]
	v_pk_mul_f32 v[34:35], v[44:45], v[0:1] op_sel_hi:[1,0]
	s_waitcnt vmcnt(14)
	v_pk_mul_f32 v[144:145], v[32:33], v[144:145]
	v_pk_mul_f32 v[146:147], v[34:35], v[146:147]
	v_cvt_pk_bf16_f32 v144, v144, v145
	v_cvt_pk_bf16_f32 v145, v146, v147
	global_store_dwordx2 v[194:195], v[144:145], off offset:1136
	v_pk_mul_f32 v[32:33], v[48:49], v[0:1] op_sel_hi:[1,0]
	s_waitcnt vmcnt(14)
	v_pk_mul_f32 v[150:151], v[20:21], v[150:151]
	v_pk_mul_f32 v[148:149], v[32:33], v[148:149]
	v_pk_mul_f32 v[20:21], v[22:23], v[0:1] op_sel_hi:[1,0]
	v_cvt_pk_bf16_f32 v148, v148, v149
	v_cvt_pk_bf16_f32 v149, v150, v151
	global_store_dwordx2 v[194:195], v[148:149], off offset:1152
	s_waitcnt vmcnt(14)
	v_pk_mul_f32 v[152:153], v[20:21], v[152:153]
	v_pk_mul_f32 v[154:155], v[18:19], v[154:155]
	v_cvt_pk_bf16_f32 v152, v152, v153
	v_cvt_pk_bf16_f32 v153, v154, v155
	global_store_dwordx2 v[194:195], v[152:153], off offset:1168
	v_pk_mul_f32 v[18:19], v[28:29], v[0:1] op_sel_hi:[1,0]
	v_pk_mul_f32 v[20:21], v[24:25], v[0:1] op_sel_hi:[1,0]
	s_waitcnt vmcnt(14)
	v_pk_mul_f32 v[156:157], v[18:19], v[156:157]
	v_pk_mul_f32 v[158:159], v[20:21], v[158:159]
	v_cvt_pk_bf16_f32 v156, v156, v157
	v_cvt_pk_bf16_f32 v157, v158, v159
	global_store_dwordx2 v[194:195], v[156:157], off offset:1184
	v_pk_mul_f32 v[18:19], v[30:31], v[0:1] op_sel_hi:[1,0]
	v_pk_mul_f32 v[20:21], v[26:27], v[0:1] op_sel_hi:[1,0]
	s_waitcnt vmcnt(14)
	v_pk_mul_f32 v[160:161], v[18:19], v[160:161]
	v_pk_mul_f32 v[162:163], v[20:21], v[162:163]
	v_cvt_pk_bf16_f32 v160, v160, v161
	v_cvt_pk_bf16_f32 v161, v162, v163
	global_store_dwordx2 v[194:195], v[160:161], off offset:1200
	s_waitcnt vmcnt(14)
	v_pk_mul_f32 v[2:3], v[2:3], v[164:165]
	v_pk_mul_f32 v[4:5], v[4:5], v[166:167]
	v_cvt_pk_bf16_f32 v2, v2, v3
	v_cvt_pk_bf16_f32 v3, v4, v5
	global_store_dwordx2 v[194:195], v[2:3], off offset:1216
	s_waitcnt vmcnt(14)
	v_pk_mul_f32 v[168:169], v[6:7], v[168:169]
	v_pk_mul_f32 v[170:171], v[8:9], v[170:171]
	v_cvt_pk_bf16_f32 v168, v168, v169
	v_cvt_pk_bf16_f32 v169, v170, v171
	global_store_dwordx2 v[194:195], v[168:169], off offset:1232
	v_pk_mul_f32 v[6:7], v[56:57], v[0:1] op_sel_hi:[1,0]
	v_pk_mul_f32 v[8:9], v[74:75], v[0:1] op_sel_hi:[1,0]
	s_waitcnt vmcnt(14)
	v_pk_mul_f32 v[172:173], v[6:7], v[172:173]
	v_pk_mul_f32 v[174:175], v[8:9], v[174:175]
	v_cvt_pk_bf16_f32 v172, v172, v173
	v_cvt_pk_bf16_f32 v173, v174, v175
	global_store_dwordx2 v[194:195], v[172:173], off offset:1248
	v_pk_mul_f32 v[6:7], v[14:15], v[0:1] op_sel_hi:[1,0]
	v_pk_mul_f32 v[8:9], v[16:17], v[0:1] op_sel_hi:[1,0]
	s_waitcnt vmcnt(14)
	v_pk_mul_f32 v[176:177], v[6:7], v[176:177]
	v_pk_mul_f32 v[178:179], v[8:9], v[178:179]
	v_cvt_pk_bf16_f32 v176, v176, v177
	v_cvt_pk_bf16_f32 v177, v178, v179
	global_store_dwordx2 v[194:195], v[176:177], off offset:1264

; template <int DQK, int DV, bool MLA>
; __device__ __forceinline__ void attn_pass(LAS unsigned char* lds, const bf16_t* Qrow, const bf16_t* K0, int pitchK, const bf16_t* KrB, const bf16_t* Vt0, int NT, int q0w,
;                                           f32x16 (&o)[DV / 32], float& l_out, int tid) {
;     ...
;     bf16x8 q[ND];
; #pragma unroll
;     for (int d0 = 0; d0 < ND; ++d0) q[d0] = *(const GAS bf16x8*)(Qrow + 16 * d0 + 8 * hi);
; #pragma unroll
;     for (int d = 0; d < NDV; ++d)
; #pragma unroll
;         for (int r = 0; r < 16; ++r) o[d][r] = 0.f;
;     float m = 0.f, l = 0.f;
;     f32x16 negm;
; #pragma unroll
;     for (int r = 0; r < 16; ++r) negm[r] = 0.f;
; #pragma unroll
;     for (int d0 = 0; d0 < ND; ++d0) asm volatile("" : "+v"(q[d0]));
;     const bf16_t* ksrc; const bf16_t* rsrc = nullptr; const bf16_t* vsrc[NVC];
;     { const int row = 8 * wid + (lane >> 3), c = (lane & 7) ^ ((row >> 1) & 7); ksrc = K0 + (size_t)row * pitchK + c * 8; }
;     if (MLA) { const int row = 16 * (wid & 3) + (lane >> 2), c = (lane & 3) ^ ((row >> 2) & 3); rsrc = KrB + (size_t)row * 32 + c * 8; }
; #pragma unroll
;     for (int j = 0; j < NVC; ++j) { const int row = 8 * (wid + 8 * j) + (lane >> 3), c = (lane & 7) ^ ((row >> 1) & 7); vsrc[j] = Vt0 + (size_t)row * 64 + c * 8; }
;     ...
;     const int xs = (r32 >> 1) & 7;
;     const int yk = (xs ^ hi) << 4;
;     const int yr = (((r32 >> 2) & 3) ^ hi) << 4;
;     bf16x8 kf[2 * ND];
;     ...
;     ATT_DMA_K(0, 0); ATT_DMA_V(0, 0); ATT_DMA_K(1, 1); ATT_DMA_V(1, 1); ATT_DMA_K(2, 2);
;     asm volatile("s_waitcnt vmcnt(0)" ::: "memory");
;     __builtin_amdgcn_s_barrier();
;     asm volatile("" ::: "memory");
;     ATT_KLOAD(0);
; __device__ __forceinline__ void attention_phase(const KP& p, LAS unsigned char* lds, unsigned char* ws, int rep) {
;     ...
;         if (tid0 == 0) *wq = atomicAdd(counter, 1u);
;         __syncthreads();
;         const unsigned u = *wq;
;         __syncthreads();
;         if (u >= (unsigned)(NUNITS / 8)) break;
;         int tid = tid_l; asm volatile("" : "+v"(tid));
;         const int lane = tid & 63, r32 = lane & 31, hi = lane >> 5, wid = tid >> 6;
;         const int code = ((const int*)(ws + WS_CTL + 32768))[u];
;         const int qb = code >> 3, sidx = code & 7;
;         const int w = sidx < 2 ? 2 * qx + sidx : 16 + 4 * qx + (sidx - 2);
;         const int NT = 4 * (qb + 1), q0w = qb * 256 + wid * 32;
.LBB0_51:
	s_or_b64 exec, exec, s[6:7]
	v_mov_b32_e32 v0, s3
	s_waitcnt lgkmcnt(0)
	s_barrier
	ds_read_b32 v0, v0
	s_movk_i32 s6, 0xbf
	s_waitcnt lgkmcnt(0)
	s_barrier
	v_cmp_lt_u32_e32 vcc, s6, v0
	s_mov_b64 s[6:7], -1
	s_cbranch_vccnz .LBB0_46
	v_lshlrev_b64 v[2:3], 2, v[0:1]
	v_mov_b32_e32 v240, v236
	v_lshl_add_u64 v[2:3], s[8:9], 0, v[2:3]
	global_load_dword v0, v[2:3], off
	v_ashrrev_i32_e32 v2, 1, v240
	v_and_b32_e32 v2, 0xffffffe0, v2
	v_and_b32_e32 v242, 31, v240
	v_bfe_u32 v239, v240, 5, 1
	v_lshrrev_b32_e32 v3, 1, v240
	v_bfe_u32 v241, v240, 3, 3
	v_lshlrev_b32_e32 v238, 7, v242
	v_bitop3_b32 v243, v3, v239, 7 bitop3:0x6c
	s_waitcnt vmcnt(0)
	v_readfirstlane_b32 s14, v0
	s_ashr_i32 s52, s14, 3
	s_and_b32 s14, s14, 7
	s_cmp_lt_u32 s14, 2
	s_cselect_b32 s53, s71, s70
	s_lshl_b32 s89, s52, 2
	v_lshl_add_u32 v202, s52, 8, v2
	s_add_i32 s53, s53, s14
	s_add_i32 s88, s89, 4
	v_ashrrev_i32_e32 v203, 31, v202
	s_cmp_gt_u32 s53, 15
	v_lshlrev_b32_e32 v0, 4, v239
	s_cbranch_scc0 .LBB0_92
	s_add_i32 s6, s53, -16
	s_lshr_b32 s16, s6, 3
	s_lshl_b64 s[44:45], s[16:17], 13
	v_lshl_add_u64 v[204:205], s[44:45], 0, v[202:203]
	v_or_b32_e32 v204, v204, v242
	v_mov_b64_e32 v[2:3], s[12:13]
	s_and_b32 s54, s53, 7
	v_mad_u64_u32 v[2:3], s[44:45], v204, s33, v[2:3]
	v_mad_i32_i24 v3, v205, s33, v3
	s_mul_i32 s44, s54, 0xc0
	s_mov_b32 s45, s17
	v_lshl_add_u64 v[2:3], v[2:3], 0, s[44:45]
	v_lshl_add_u64 v[2:3], v[2:3], 0, v[0:1]
	global_load_dwordx4 v[82:85], v[2:3], off
	global_load_dwordx4 v[86:89], v[2:3], off offset:32
	global_load_dwordx4 v[90:93], v[2:3], off offset:64
	global_load_dwordx4 v[94:97], v[2:3], off offset:96
	global_load_dwordx4 v[98:101], v[2:3], off offset:128
	global_load_dwordx4 v[102:105], v[2:3], off offset:160
	s_lshl_b64 s[6:7], s[16:17], 19
	s_add_u32 s14, s61, s6
	s_addc_u32 s15, s62, s7
	s_lshl_b32 s6, s16, 7
	s_mov_b32 s7, s17
	s_lshl_b64 s[6:7], s[6:7], 16
	s_add_u32 s6, s63, s6
	s_addc_u32 s7, s64, s7
	s_lshl_b32 s46, s54, 13
	s_add_u32 s6, s6, s46
	s_addc_u32 s7, s7, 0
	s_lshl_b64 s[44:45], s[16:17], 23
	s_add_u32 s16, s59, s44
	s_addc_u32 s45, s60, s45
	s_lshl_b32 s44, s54, 7
	s_add_u32 s44, s16, s44
	v_readfirstlane_b32 s16, v240
	s_addc_u32 s45, s45, 0
	s_ashr_i32 s16, s16, 6
	v_lshl_or_b32 v2, s16, 3, v241
	v_lshrrev_b32_e32 v3, 1, v2
	v_xor_b32_e32 v6, v3, v240
	v_ashrrev_i32_e32 v3, 31, v2
	v_lshlrev_b64 v[4:5], 10, v[2:3]
	v_lshlrev_b32_e32 v6, 4, v6
	v_lshl_add_u64 v[4:5], s[44:45], 0, v[4:5]
	v_and_b32_e32 v6, 0x70, v6
	v_mov_b32_e32 v7, v1
	v_lshl_add_u64 v[50:51], v[4:5], 0, v[6:7]
	v_lshrrev_b32_e32 v4, 4, v240
	v_xor_b32_e32 v8, v4, v240
	v_lshlrev_b32_e32 v4, 4, v240
	s_lshl_b32 s16, s16, 10
	v_and_b32_e32 v4, 0x3c0, v4
	s_and_b32 s44, s16, 0xc00
	v_or_b32_e32 v4, s44, v4
	v_mov_b32_e32 v5, v1
	v_lshlrev_b32_e32 v8, 4, v8
	v_lshl_add_u64 v[4:5], s[14:15], 0, v[4:5]
	v_and_b32_e32 v8, 48, v8
	v_mov_b32_e32 v9, v1
	v_lshl_add_u64 v[52:53], v[4:5], 0, v[8:9]
	v_lshl_add_u64 v[4:5], s[6:7], 0, v[6:7]
	s_add_i32 s16, s16, 0
	v_lshlrev_b64 v[2:3], 7, v[2:3]
	v_lshl_add_u64 v[54:55], v[4:5], 0, v[2:3]
	s_add_i32 s56, s16, 0xc000
	v_lshl_add_u64 v[2:3], v[50:51], 0, s[18:19]
	v_lshlrev_b32_e32 v244, 4, v243
	s_mov_b32 s6, m0
	s_mov_b32 m0, s16
	s_nop 0
	global_load_lds_dwordx4 v[50:51], off
	s_mov_b32 m0, s6
	s_add_i32 s6, s44, 0
	s_add_i32 s55, s6, 0x8000
	s_mov_b32 s7, m0
	s_mov_b32 m0, s55
	s_nop 0
	global_load_lds_dwordx4 v[52:53], off
	s_mov_b32 m0, s7
	s_nop 0
	s_mov_b32 s7, m0
	s_mov_b32 m0, s56
	s_nop 0
	global_load_lds_dwordx4 v[54:55], off
	s_mov_b32 m0, s7
	s_add_i32 s7, s16, 0x2000
	s_mov_b32 s14, m0
	s_mov_b32 m0, s7
	s_nop 0
	global_load_lds_dwordx4 v[2:3], off
	s_mov_b32 m0, s14
	v_lshl_add_u64 v[2:3], v[52:53], 0, s[20:21]
	s_add_i32 s7, s6, 0x9000
	s_mov_b32 s14, m0
	s_mov_b32 m0, s7
	s_nop 0
	global_load_lds_dwordx4 v[2:3], off
	s_mov_b32 m0, s14
	v_lshl_add_u64 v[2:3], v[54:55], 0, s[18:19]
	s_add_i32 s7, s16, 0xe000
	s_mov_b32 s14, m0
	s_mov_b32 m0, s7
	s_nop 0
	global_load_lds_dwordx4 v[2:3], off
	s_mov_b32 m0, s14
	v_lshl_add_u64 v[2:3], v[50:51], 0, s[22:23]
	s_add_i32 s7, s16, 0x4000
	s_mov_b32 s14, m0
	s_mov_b32 m0, s7
	s_nop 0
	global_load_lds_dwordx4 v[2:3], off
	s_mov_b32 m0, s14
	v_lshl_add_u64 v[2:3], v[52:53], 0, s[24:25]
	s_add_i32 s7, s6, 0xa000
	s_mov_b32 s14, m0
	s_mov_b32 m0, s7
	s_nop 0
	global_load_lds_dwordx4 v[2:3], off
	s_mov_b32 m0, s14
	s_waitcnt vmcnt(0)
	s_barrier
	s_cmp_lt_i32 s52, 0
	s_cbranch_scc1 .LBB0_166
	v_lshrrev_b32_e32 v2, 2, v240
	v_bitop3_b32 v2, v2, v239, 3 bitop3:0x6c
	v_lshlrev_b32_e32 v245, 4, v2
	v_add_u32_e32 v246, 0, v238
	v_lshlrev_b32_e32 v56, 6, v242
	v_sub_u32_e32 v247, v246, v56
	v_xor_b32_e32 v248, 32, v245
	v_xor_b32_e32 v249, 0x60, v244
	v_xor_b32_e32 v250, 64, v244
	v_xor_b32_e32 v251, 32, v244
	v_add_u32_e32 v57, v247, v248
	v_add_u32_e32 v58, v247, v245
	v_add_u32_e32 v59, v246, v249
	v_add_u32_e32 v60, v246, v250
	v_add_u32_e32 v61, v246, v251
	v_add_u32_e32 v62, v246, v244
	ds_read_b128 v[106:109], v57 offset:34816
	ds_read_b128 v[118:121], v57 offset:32768
	ds_read_b128 v[110:113], v58 offset:34816
	ds_read_b128 v[114:117], v58 offset:32768
	ds_read_b128 v[122:125], v59 offset:4096
	ds_read_b128 v[126:129], v59
	ds_read_b128 v[130:133], v60 offset:4096
	ds_read_b128 v[134:137], v60
	ds_read_b128 v[138:141], v61 offset:4096
	ds_read_b128 v[142:145], v61
	ds_read_b128 v[146:149], v62 offset:4096
	ds_read_b128 v[150:153], v62
	v_lshl_add_u64 v[2:3], v[50:51], 0, s[26:27]
	s_add_i32 s7, s16, 0x6000
	s_mov_b32 s14, m0
	s_mov_b32 m0, s7
	s_nop 0
	global_load_lds_dwordx4 v[2:3], off
	s_mov_b32 m0, s14
	s_mov_b64 s[14:15], 0x3000
	v_lshl_add_u64 v[2:3], v[52:53], 0, s[14:15]
	s_add_i32 s6, s6, 0xb000
	s_mov_b32 s7, m0
	s_mov_b32 m0, s6
	s_nop 0
	global_load_lds_dwordx4 v[2:3], off
	s_mov_b32 m0, s7
	v_lshl_add_u64 v[2:3], v[54:55], 0, s[22:23]
	s_add_i32 s6, s16, 0x10000
	s_mov_b32 s7, m0
	s_mov_b32 m0, s6
	s_nop 0
	global_load_lds_dwordx4 v[2:3], off
	s_mov_b32 m0, s7
	v_mov_b32_e32 v34, v1
	v_mov_b32_e32 v35, v1
	v_mov_b32_e32 v36, v1
	v_mov_b32_e32 v37, v1
	v_mov_b32_e32 v38, v1
	v_mov_b32_e32 v39, v1
	v_mov_b32_e32 v40, v1
	v_mov_b32_e32 v41, v1
	v_mov_b32_e32 v42, v1
	v_mov_b32_e32 v43, v1
	v_mov_b32_e32 v44, v1
	v_mov_b32_e32 v45, v1
	v_mov_b32_e32 v46, v1
	v_mov_b32_e32 v47, v1
	v_mov_b32_e32 v48, v1
	v_mov_b32_e32 v49, v1
	v_mov_b64_e32 v[2:3], v[34:35]
	v_or_b32_e32 v252, v202, v242
	v_cmp_lt_i32_e64 s[48:49], -1, v202
	v_mov_b32_e32 v207, 0
	v_mov_b32_e32 v206, 0
	v_mov_b64_e32 v[4:5], v[36:37]
	v_mov_b64_e32 v[6:7], v[38:39]
	v_mov_b64_e32 v[8:9], v[40:41]
	v_mov_b64_e32 v[10:11], v[42:43]
	v_mov_b64_e32 v[12:13], v[44:45]
	v_mov_b64_e32 v[14:15], v[46:47]
	v_mov_b64_e32 v[16:17], v[48:49]
	s_and_saveexec_b64 s[44:45], s[48:49]
	s_cbranch_execz .LBB0_58
; #define MFMA32(a, b, c) __builtin_amdgcn_mfma_f32_32x32x16_bf16((a), (b), (c), 0, 0, 0)
; #define PV_IDX(g) (((g) & 1) * 4 + PV_KS(g))
; template <int DQK, int DV, bool MLA>
; __device__ __forceinline__ void attn_pass(LAS unsigned char* lds, const bf16_t* Qrow, const bf16_t* K0, int pitchK, const bf16_t* KrB, const bf16_t* Vt0, int NT, int q0w,
;                                           f32x16 (&o)[DV / 32], float& l_out, int tid) {
;     ...
;             __builtin_amdgcn_s_setprio(1);
; #pragma unroll
;             for (int d0 = 0; d0 < ND; ++d0) { s0 = MFMA32(kf[2 * d0], q[d0], s0); s1 = MFMA32(kf[2 * d0 + 1], q[d0], s1); }
;             __builtin_amdgcn_s_setprio(0);
;             __builtin_amdgcn_sched_barrier(0);
;             if (t + 1 < NT) ATT_KLOAD((t + 1) & 3);
;             bf16x8 vf[8];
;             if (pend) {
; #pragma unroll
;                 for (int g = 0; g < 8; ++g) vf[PV_IDX(g)] = VFRAG(vp, PV_D(g), PV_KS(g));
;             }
;             __builtin_amdgcn_sched_barrier(0);
;             if (64 * t + 63 > q0w) {
;                 int hi_l = hi; asm volatile("" : "+v"(hi_l));
;                 const int qrow = q0w + r32, kb0 = 64 * t + 4 * hi_l;
; #pragma unroll
;                 for (int r = 0; r < 16; ++r) { const int kv = kb0 + (r & 3) + 8 * (r >> 2); if (kv > qrow) s0[r] = -INFINITY; if (kv + 32 > qrow) s1[r] = -INFINITY; }
;             }
	s_setprio 1
	s_waitcnt lgkmcnt(0)
	v_mfma_f32_32x32x16_bf16 v[18:33], v[150:153], v[82:85], 0
	v_mfma_f32_32x32x16_bf16 v[2:17], v[146:149], v[82:85], 0
	v_mfma_f32_32x32x16_bf16 v[18:33], v[142:145], v[86:89], v[18:33]
	v_mfma_f32_32x32x16_bf16 v[2:17], v[138:141], v[86:89], v[2:17]
	v_mfma_f32_32x32x16_bf16 v[18:33], v[134:137], v[90:93], v[18:33]
	v_mfma_f32_32x32x16_bf16 v[2:17], v[130:133], v[90:93], v[2:17]
	v_mfma_f32_32x32x16_bf16 v[18:33], v[126:129], v[94:97], v[18:33]
	v_mfma_f32_32x32x16_bf16 v[2:17], v[122:125], v[94:97], v[2:17]
	v_mfma_f32_32x32x16_bf16 v[18:33], v[114:117], v[98:101], v[18:33]
	v_mfma_f32_32x32x16_bf16 v[2:17], v[110:113], v[98:101], v[2:17]
	v_mfma_f32_32x32x16_bf16 v[18:33], v[118:121], v[102:105], v[18:33]
	v_mfma_f32_32x32x16_bf16 v[2:17], v[106:109], v[102:105], v[2:17]
	s_setprio 0
	ds_read_b128 v[150:153], v62 offset:8192
	ds_read_b128 v[146:149], v62 offset:12288
	ds_read_b128 v[142:145], v61 offset:8192
	ds_read_b128 v[138:141], v61 offset:12288
	ds_read_b128 v[134:137], v60 offset:8192
	ds_read_b128 v[130:133], v60 offset:12288
	ds_read_b128 v[126:129], v59 offset:8192
	ds_read_b128 v[122:125], v59 offset:12288
	ds_read_b128 v[114:117], v58 offset:36864
	ds_read_b128 v[110:113], v58 offset:38912
	ds_read_b128 v[106:109], v57 offset:38912
	ds_read_b128 v[118:121], v57 offset:36864
	v_cmp_gt_u32_e32 vcc, 63, v202
	s_and_saveexec_b64 s[6:7], vcc
	s_cbranch_execz .LBB0_57
	v_mov_b32_e32 v34, v239
	s_nop 0
	v_lshlrev_b32_e32 v34, 2, v34
	v_add_u32_e32 v35, 32, v34
	v_cmp_le_i32_e32 vcc, v35, v252
	v_add_u32_e32 v35, 33, v34
	s_nop 0
	v_cndmask_b32_e32 v2, v220, v2, vcc
	v_cmp_lt_i32_e32 vcc, v34, v252
	s_nop 1
	v_cndmask_b32_e32 v19, v220, v19, vcc
	v_cmp_le_i32_e32 vcc, v34, v252
	s_nop 1
	v_cndmask_b32_e32 v18, v220, v18, vcc
	v_cmp_le_i32_e32 vcc, v35, v252
	v_or_b32_e32 v35, 2, v34
	s_nop 0
	v_cndmask_b32_e32 v3, v220, v3, vcc
	v_cmp_le_i32_e32 vcc, v35, v252
	v_add_u32_e32 v35, 34, v34
	s_nop 0
	v_cndmask_b32_e32 v20, v220, v20, vcc
	v_cmp_le_i32_e32 vcc, v35, v252
	v_or_b32_e32 v35, 3, v34
	s_nop 0
	v_cndmask_b32_e32 v4, v220, v4, vcc
	v_cmp_le_i32_e32 vcc, v35, v252
	v_add_u32_e32 v35, 35, v34
	s_nop 0
	v_cndmask_b32_e32 v21, v220, v21, vcc
	v_cmp_le_i32_e32 vcc, v35, v252
	v_add_u32_e32 v35, 8, v34
	s_nop 0
	v_cndmask_b32_e32 v5, v220, v5, vcc
	v_cmp_le_i32_e32 vcc, v35, v252
	v_add_u32_e32 v35, 40, v34
	s_nop 0
	v_cndmask_b32_e32 v22, v220, v22, vcc
	v_cmp_le_i32_e32 vcc, v35, v252
	v_add_u32_e32 v35, 9, v34
	s_nop 0
	v_cndmask_b32_e32 v6, v220, v6, vcc
	v_cmp_le_i32_e32 vcc, v35, v252
	v_add_u32_e32 v35, 41, v34
	s_nop 0
	v_cndmask_b32_e32 v23, v220, v23, vcc
	v_cmp_le_i32_e32 vcc, v35, v252
	v_add_u32_e32 v35, 10, v34
	s_nop 0
	v_cndmask_b32_e32 v7, v220, v7, vcc
	v_cmp_le_i32_e32 vcc, v35, v252
	v_add_u32_e32 v35, 42, v34
	s_nop 0
	v_cndmask_b32_e32 v24, v220, v24, vcc
	v_cmp_le_i32_e32 vcc, v35, v252
	v_add_u32_e32 v35, 11, v34
	s_nop 0
	v_cndmask_b32_e32 v8, v220, v8, vcc
	v_cmp_le_i32_e32 vcc, v35, v252
	v_add_u32_e32 v35, 43, v34
	s_nop 0
	v_cndmask_b32_e32 v25, v220, v25, vcc
	v_cmp_le_i32_e32 vcc, v35, v252
	v_add_u32_e32 v35, 16, v34
	s_nop 0
	v_cndmask_b32_e32 v9, v220, v9, vcc
	v_cmp_le_i32_e32 vcc, v35, v252
	v_add_u32_e32 v35, 48, v34
	s_nop 0
	v_cndmask_b32_e32 v26, v220, v26, vcc
	v_cmp_le_i32_e32 vcc, v35, v252
	v_add_u32_e32 v35, 17, v34
	s_nop 0
	v_cndmask_b32_e32 v10, v220, v10, vcc
	v_cmp_le_i32_e32 vcc, v35, v252
	v_add_u32_e32 v35, 49, v34
	s_nop 0
	v_cndmask_b32_e32 v27, v220, v27, vcc
	v_cmp_le_i32_e32 vcc, v35, v252
	v_add_u32_e32 v35, 18, v34
	s_nop 0
	v_cndmask_b32_e32 v11, v220, v11, vcc
	v_cmp_le_i32_e32 vcc, v35, v252
	v_add_u32_e32 v35, 50, v34
	s_nop 0
	v_cndmask_b32_e32 v28, v220, v28, vcc
	v_cmp_le_i32_e32 vcc, v35, v252
	v_add_u32_e32 v35, 19, v34
	s_nop 0
	v_cndmask_b32_e32 v12, v220, v12, vcc
	v_cmp_le_i32_e32 vcc, v35, v252
	v_add_u32_e32 v35, 51, v34
	s_nop 0
	v_cndmask_b32_e32 v29, v220, v29, vcc
	v_cmp_le_i32_e32 vcc, v35, v252
	v_add_u32_e32 v35, 24, v34
	s_nop 0
	v_cndmask_b32_e32 v13, v220, v13, vcc
	v_cmp_le_i32_e32 vcc, v35, v252
	v_add_u32_e32 v35, 56, v34
	s_nop 0
	v_cndmask_b32_e32 v30, v220, v30, vcc
	v_cmp_le_i32_e32 vcc, v35, v252
	v_add_u32_e32 v35, 25, v34
	s_nop 0
	v_cndmask_b32_e32 v14, v220, v14, vcc
	v_cmp_le_i32_e32 vcc, v35, v252
	v_add_u32_e32 v35, 57, v34
	s_nop 0
	v_cndmask_b32_e32 v31, v220, v31, vcc
	v_cmp_le_i32_e32 vcc, v35, v252
	v_add_u32_e32 v35, 26, v34
	s_nop 0
	v_cndmask_b32_e32 v15, v220, v15, vcc
	v_cmp_le_i32_e32 vcc, v35, v252
	v_add_u32_e32 v35, 58, v34
	s_nop 0
	v_cndmask_b32_e32 v32, v220, v32, vcc
	v_cmp_le_i32_e32 vcc, v35, v252
	v_add_u32_e32 v35, 27, v34
	v_add_u32_e32 v34, 59, v34
	v_cndmask_b32_e32 v16, v220, v16, vcc
	v_cmp_le_i32_e32 vcc, v35, v252
	s_nop 1
	v_cndmask_b32_e32 v33, v220, v33, vcc
	v_cmp_le_i32_e32 vcc, v34, v252
	s_nop 1
	v_cndmask_b32_e32 v17, v220, v17, vcc

; template <int DQK, int DV, bool MLA>
; __device__ __forceinline__ void attn_pass(LAS unsigned char* lds, const bf16_t* Qrow, const bf16_t* K0, int pitchK, const bf16_t* KrB, const bf16_t* Vt0, int NT, int q0w,
;                                           f32x16 (&o)[DV / 32], float& l_out, int tid) {
;     ...
;     bf16x8 q[ND];
; #pragma unroll
;     for (int d0 = 0; d0 < ND; ++d0) q[d0] = *(const GAS bf16x8*)(Qrow + 16 * d0 + 8 * hi);
; #pragma unroll
;     for (int d = 0; d < NDV; ++d)
; #pragma unroll
;         for (int r = 0; r < 16; ++r) o[d][r] = 0.f;
;     float m = 0.f, l = 0.f;
;     f32x16 negm;
; #pragma unroll
;     for (int r = 0; r < 16; ++r) negm[r] = 0.f;
; #pragma unroll
;     for (int d0 = 0; d0 < ND; ++d0) asm volatile("" : "+v"(q[d0]));
;     const bf16_t* ksrc; const bf16_t* rsrc = nullptr; const bf16_t* vsrc[NVC];
;     { const int row = 8 * wid + (lane >> 3), c = (lane & 7) ^ ((row >> 1) & 7); ksrc = K0 + (size_t)row * pitchK + c * 8; }
;     if (MLA) { const int row = 16 * (wid & 3) + (lane >> 2), c = (lane & 3) ^ ((row >> 2) & 3); rsrc = KrB + (size_t)row * 32 + c * 8; }
; #pragma unroll
;     for (int j = 0; j < NVC; ++j) { const int row = 8 * (wid + 8 * j) + (lane >> 3), c = (lane & 7) ^ ((row >> 1) & 7); vsrc[j] = Vt0 + (size_t)row * 64 + c * 8; }
;     ...
;     const int xs = (r32 >> 1) & 7;
;     const int yk = (xs ^ hi) << 4;
;     const int yr = (((r32 >> 2) & 3) ^ hi) << 4;
;     bf16x8 kf[2 * ND];
;     ...
;     ATT_DMA_K(0, 0); ATT_DMA_V(0, 0); ATT_DMA_K(1, 1); ATT_DMA_V(1, 1); ATT_DMA_K(2, 2);
;     asm volatile("s_waitcnt vmcnt(0)" ::: "memory");
;     __builtin_amdgcn_s_barrier();
;     asm volatile("" ::: "memory");
;     ATT_KLOAD(0);
; __device__ __forceinline__ void attention_phase(const KP& p, LAS unsigned char* lds, unsigned char* ws, int rep) {
;     ...
;             const int b = w >> 2, h = w & 3; const size_t rb = (size_t)b * SEQ;
;             const bf16_t* Qd = (const bf16_t*)(ws + WS_QD); const bf16_t* Kd = (const bf16_t*)(ws + WS_KD); const bf16_t* Vt = (const bf16_t*)(ws + WS_VTD) + ((size_t)(b * (SEQ / 64)) * 512 + h * 128) * 64;
;             bf16_t* yo = ((bf16_t*)p.out) + (rb + q0w + r32) * 1024 + 512 + h * 128;
;             {
;                 f32x16 oA[4]; float lA;
;                 attn_pass<64, 128, false>(lds, Qd + (rb + q0w + r32) * 512 + (2 * h) * 64, Kd + rb * 512 + (2 * h) * 64, 512, nullptr, Vt, NT, q0w, oA, lA, tid);
.LBB0_92:
	s_and_b64 vcc, exec, s[6:7]
	s_cbranch_vccz .LBB0_45
	s_lshr_b32 s6, s53, 2
	s_lshl_b32 s7, s53, 7
	s_lshl_b32 s16, s6, 13
	s_lshl_b32 s6, s6, 23
	s_and_b32 s7, s7, 0x180
	s_add_u32 s14, s68, s6
	s_waitcnt lgkmcnt(3)
	v_lshl_add_u64 v[194:195], s[16:17], 0, v[202:203]
	s_addc_u32 s15, s69, 0
	s_lshl_b32 s44, s7, 7
	v_or_b32_e32 v194, v194, v242
	s_add_u32 s44, s14, s44
	v_lshlrev_b64 v[2:3], 10, v[194:195]
	s_addc_u32 s45, s15, 0
	v_lshl_add_u64 v[2:3], s[40:41], 0, v[2:3]
	s_lshl_b32 s16, s7, 1
	v_lshl_add_u64 v[2:3], v[2:3], 0, s[16:17]
	v_lshl_add_u64 v[196:197], v[2:3], 0, v[0:1]
	global_load_dwordx4 v[114:117], v[196:197], off
	s_waitcnt lgkmcnt(0)
	global_load_dwordx4 v[118:121], v[196:197], off offset:32
	global_load_dwordx4 v[122:125], v[196:197], off offset:64
	global_load_dwordx4 v[126:129], v[196:197], off offset:96
	s_add_u32 s6, s65, s6
	s_addc_u32 s14, s67, 0
	v_readfirstlane_b32 s7, v240
	s_add_u32 s48, s6, s16
	s_addc_u32 s49, s14, 0
	s_ashr_i32 s6, s7, 6
	v_lshl_or_b32 v2, s6, 3, v241
	v_lshrrev_b32_e32 v0, 1, v2
	v_ashrrev_i32_e32 v3, 31, v2
	v_xor_b32_e32 v0, v0, v240
	v_lshlrev_b64 v[4:5], 10, v[2:3]
	v_lshlrev_b32_e32 v0, 4, v0
	s_lshl_b32 s90, s6, 10
	v_lshlrev_b64 v[2:3], 7, v[2:3]
	v_lshl_add_u64 v[4:5], s[48:49], 0, v[4:5]
	v_and_b32_e32 v0, 0x70, v0
	s_add_i32 s90, s90, 0
	v_lshl_add_u64 v[2:3], s[44:45], 0, v[2:3]
	v_lshl_add_u64 v[50:51], v[4:5], 0, v[0:1]
	s_add_i32 s91, s90, 0x8000
	v_lshl_add_u64 v[52:53], v[2:3], 0, v[0:1]
	s_add_i32 s6, s90, 0xa000
	v_lshl_add_u64 v[54:55], v[52:53], 0, s[24:25]
	s_add_i32 s7, s90, 0x2000
	v_lshl_add_u64 v[2:3], v[50:51], 0, s[18:19]
	s_add_i32 s14, s90, 0xc000
	v_lshl_add_u64 v[4:5], v[52:53], 0, s[18:19]
	s_add_i32 s15, s90, 0xe000
	v_lshl_add_u64 v[6:7], v[52:53], 0, s[30:31]
	s_add_i32 s50, s90, 0x4000
	v_lshl_add_u64 v[8:9], v[50:51], 0, s[22:23]
	v_lshlrev_b32_e32 v210, 4, v243
	v_add_u32_e32 v211, 0, v238
	v_xor_b32_e32 v209, 32, v210
	v_xor_b32_e32 v208, 64, v210
	v_xor_b32_e32 v203, 0x60, v210
	s_cmp_gt_i32 s52, -1
	v_add_u32_e32 v213, v211, v203
	v_add_u32_e32 v214, v211, v208
	s_cselect_b64 s[46:47], -1, 0
	s_cmp_lt_i32 s52, 0
	v_add_u32_e32 v215, v211, v209
	v_add_u32_e32 v243, v211, v210
	v_or_b32_e32 v212, v202, v242
	v_cmp_lt_i32_e64 s[54:55], -1, v202
	s_mov_b32 s51, m0
	s_mov_b32 m0, s90
	s_nop 0
	global_load_lds_dwordx4 v[50:51], off
	s_mov_b32 m0, s51
	s_nop 0
	s_mov_b32 s51, m0
	s_mov_b32 m0, s91
	s_nop 0
	global_load_lds_dwordx4 v[52:53], off
	s_mov_b32 m0, s51
	s_nop 0
	s_mov_b32 s51, m0
	s_mov_b32 m0, s6
	s_nop 0
	global_load_lds_dwordx4 v[54:55], off
	s_mov_b32 m0, s51
	s_mov_b32 s6, m0
	s_mov_b32 m0, s7
	s_nop 0
	global_load_lds_dwordx4 v[2:3], off
	s_mov_b32 m0, s6
	s_nop 0
	s_mov_b32 s6, m0
	s_mov_b32 m0, s14
	s_nop 0
	global_load_lds_dwordx4 v[4:5], off
	s_mov_b32 m0, s6
	s_nop 0
	s_mov_b32 s6, m0
	s_mov_b32 m0, s15
	s_nop 0
	global_load_lds_dwordx4 v[6:7], off
	s_mov_b32 m0, s6
	s_nop 0
	s_mov_b32 s6, m0
	s_mov_b32 m0, s50
	s_nop 0
	global_load_lds_dwordx4 v[8:9], off
	s_mov_b32 m0, s6
	s_waitcnt vmcnt(0)
	s_barrier
	s_cbranch_scc1 .LBB0_167
	ds_read_b128 v[130:133], v213 offset:4096
	ds_read_b128 v[134:137], v213
	ds_read_b128 v[138:141], v214 offset:4096
	ds_read_b128 v[142:145], v214
	ds_read_b128 v[146:149], v215 offset:4096
	ds_read_b128 v[150:153], v215
	ds_read_b128 v[154:157], v243 offset:4096
	ds_read_b128 v[158:161], v243
	v_lshl_add_u64 v[2:3], v[50:51], 0, s[26:27]
	s_add_i32 s6, s90, 0x6000
	s_mov_b32 s7, m0
	s_mov_b32 m0, s6
	s_nop 0
	global_load_lds_dwordx4 v[2:3], off
	s_mov_b32 m0, s7
	v_lshl_add_u64 v[2:3], v[54:55], 0, s[22:23]
	v_lshl_add_u64 v[4:5], v[52:53], 0, s[22:23]
	s_add_i32 s6, s90, 0x10000
	s_mov_b32 s7, m0
	s_mov_b32 m0, s6
	s_nop 0
	global_load_lds_dwordx4 v[4:5], off
	s_mov_b32 m0, s7
	s_add_i32 s6, s90, 0x12000
	s_mov_b32 s7, m0
	s_mov_b32 m0, s6
	s_nop 0
	global_load_lds_dwordx4 v[2:3], off
	s_mov_b32 m0, s7
	v_mov_b32_e32 v2, v1
	v_mov_b32_e32 v3, v1
	v_mov_b32_e32 v4, v1
	v_mov_b32_e32 v5, v1
	v_mov_b32_e32 v6, v1
	v_mov_b32_e32 v7, v1
	v_mov_b32_e32 v8, v1
	v_mov_b32_e32 v9, v1
	v_mov_b32_e32 v10, v1
	v_mov_b32_e32 v11, v1
	v_mov_b32_e32 v12, v1
	v_mov_b32_e32 v13, v1
	v_mov_b32_e32 v14, v1
	v_mov_b32_e32 v15, v1
	v_mov_b32_e32 v0, v1
	v_mov_b64_e32 v[16:17], v[14:15]
	v_mov_b32_e32 v244, 0
	v_mov_b32_e32 v242, 0
	v_mov_b64_e32 v[14:15], v[12:13]
	v_mov_b64_e32 v[12:13], v[10:11]
	v_mov_b64_e32 v[10:11], v[8:9]
	v_mov_b64_e32 v[8:9], v[6:7]
	v_mov_b64_e32 v[6:7], v[4:5]
	v_mov_b64_e32 v[4:5], v[2:3]
	v_mov_b64_e32 v[2:3], v[0:1]
	s_and_saveexec_b64 s[50:51], s[54:55]
	s_cbranch_execz .LBB0_98
; #define MFMA32(a, b, c) __builtin_amdgcn_mfma_f32_32x32x16_bf16((a), (b), (c), 0, 0, 0)
; #define PV_IDX(g) (((g) & 1) * 4 + PV_KS(g))
; template <int DQK, int DV, bool MLA>
; __device__ __forceinline__ void attn_pass(LAS unsigned char* lds, const bf16_t* Qrow, const bf16_t* K0, int pitchK, const bf16_t* KrB, const bf16_t* Vt0, int NT, int q0w,
;                                           f32x16 (&o)[DV / 32], float& l_out, int tid) {
;     ...
;             __builtin_amdgcn_s_setprio(1);
; #pragma unroll
;             for (int d0 = 0; d0 < ND; ++d0) { s0 = MFMA32(kf[2 * d0], q[d0], s0); s1 = MFMA32(kf[2 * d0 + 1], q[d0], s1); }
;             __builtin_amdgcn_s_setprio(0);
;             __builtin_amdgcn_sched_barrier(0);
;             if (t + 1 < NT) ATT_KLOAD((t + 1) & 3);
;             bf16x8 vf[8];
;             if (pend) {
; #pragma unroll
;                 for (int g = 0; g < 8; ++g) vf[PV_IDX(g)] = VFRAG(vp, PV_D(g), PV_KS(g));
;             }
;             __builtin_amdgcn_sched_barrier(0);
;             if (64 * t + 63 > q0w) {
;                 int hi_l = hi; asm volatile("" : "+v"(hi_l));
;                 const int qrow = q0w + r32, kb0 = 64 * t + 4 * hi_l;
; #pragma unroll
;                 for (int r = 0; r < 16; ++r) { const int kv = kb0 + (r & 3) + 8 * (r >> 2); if (kv > qrow) s0[r] = -INFINITY; if (kv + 32 > qrow) s1[r] = -INFINITY; }
;             }
	s_setprio 1
	s_waitcnt lgkmcnt(0)
	v_mfma_f32_32x32x16_bf16 v[34:49], v[158:161], v[114:117], 0
	v_mfma_f32_32x32x16_bf16 v[18:33], v[154:157], v[114:117], 0
	v_mfma_f32_32x32x16_bf16 v[34:49], v[150:153], v[118:121], v[34:49]
	v_mfma_f32_32x32x16_bf16 v[18:33], v[146:149], v[118:121], v[18:33]
	v_mfma_f32_32x32x16_bf16 v[34:49], v[142:145], v[122:125], v[34:49]
	v_mfma_f32_32x32x16_bf16 v[18:33], v[138:141], v[122:125], v[18:33]
	v_mfma_f32_32x32x16_bf16 v[34:49], v[134:137], v[126:129], v[34:49]
	v_mfma_f32_32x32x16_bf16 v[18:33], v[130:133], v[126:129], v[18:33]
	s_setprio 0
	ds_read_b128 v[158:161], v243 offset:8192
	ds_read_b128 v[154:157], v243 offset:12288
	ds_read_b128 v[150:153], v215 offset:8192
	ds_read_b128 v[146:149], v215 offset:12288
	ds_read_b128 v[142:145], v214 offset:8192
	ds_read_b128 v[138:141], v214 offset:12288
	ds_read_b128 v[134:137], v213 offset:8192
	ds_read_b128 v[130:133], v213 offset:12288
	v_cmp_gt_u32_e32 vcc, 63, v202
	s_and_saveexec_b64 s[6:7], vcc
	s_cbranch_execz .LBB0_97
	v_mov_b32_e32 v0, v239
	s_nop 0
	v_lshlrev_b32_e32 v0, 2, v0
	v_add_u32_e32 v2, 32, v0
	v_cmp_le_i32_e32 vcc, v2, v212
	v_add_u32_e32 v2, 33, v0
	s_nop 0
	v_cndmask_b32_e32 v18, v220, v18, vcc
	v_cmp_lt_i32_e32 vcc, v0, v212
	s_nop 1
	v_cndmask_b32_e32 v35, v220, v35, vcc
	v_cmp_le_i32_e32 vcc, v0, v212
	s_nop 1
	v_cndmask_b32_e32 v34, v220, v34, vcc
	v_cmp_le_i32_e32 vcc, v2, v212
	v_or_b32_e32 v2, 2, v0
	s_nop 0
	v_cndmask_b32_e32 v19, v220, v19, vcc
	v_cmp_le_i32_e32 vcc, v2, v212
	v_add_u32_e32 v2, 34, v0
	s_nop 0
	v_cndmask_b32_e32 v36, v220, v36, vcc
	v_cmp_le_i32_e32 vcc, v2, v212
	v_or_b32_e32 v2, 3, v0
	s_nop 0
	v_cndmask_b32_e32 v20, v220, v20, vcc
	v_cmp_le_i32_e32 vcc, v2, v212
	v_add_u32_e32 v2, 35, v0
	s_nop 0
	v_cndmask_b32_e32 v37, v220, v37, vcc
	v_cmp_le_i32_e32 vcc, v2, v212
	v_add_u32_e32 v2, 8, v0
	s_nop 0
	v_cndmask_b32_e32 v21, v220, v21, vcc
	v_cmp_le_i32_e32 vcc, v2, v212
	v_add_u32_e32 v2, 40, v0
	s_nop 0
	v_cndmask_b32_e32 v38, v220, v38, vcc
	v_cmp_le_i32_e32 vcc, v2, v212
	v_add_u32_e32 v2, 9, v0
	s_nop 0
	v_cndmask_b32_e32 v22, v220, v22, vcc
	v_cmp_le_i32_e32 vcc, v2, v212
	v_add_u32_e32 v2, 41, v0
	s_nop 0
	v_cndmask_b32_e32 v39, v220, v39, vcc
	v_cmp_le_i32_e32 vcc, v2, v212
	v_add_u32_e32 v2, 10, v0
	s_nop 0
	v_cndmask_b32_e32 v23, v220, v23, vcc
	v_cmp_le_i32_e32 vcc, v2, v212
	v_add_u32_e32 v2, 42, v0
	s_nop 0
	v_cndmask_b32_e32 v40, v220, v40, vcc
	v_cmp_le_i32_e32 vcc, v2, v212
	v_add_u32_e32 v2, 11, v0
	s_nop 0
	v_cndmask_b32_e32 v24, v220, v24, vcc
	v_cmp_le_i32_e32 vcc, v2, v212
	v_add_u32_e32 v2, 43, v0
	s_nop 0
	v_cndmask_b32_e32 v41, v220, v41, vcc
	v_cmp_le_i32_e32 vcc, v2, v212
	v_add_u32_e32 v2, 16, v0
	s_nop 0
	v_cndmask_b32_e32 v25, v220, v25, vcc
	v_cmp_le_i32_e32 vcc, v2, v212
	v_add_u32_e32 v2, 48, v0
	s_nop 0
	v_cndmask_b32_e32 v42, v220, v42, vcc
	v_cmp_le_i32_e32 vcc, v2, v212
	v_add_u32_e32 v2, 17, v0
	s_nop 0
	v_cndmask_b32_e32 v26, v220, v26, vcc
	v_cmp_le_i32_e32 vcc, v2, v212
	v_add_u32_e32 v2, 49, v0
	s_nop 0
	v_cndmask_b32_e32 v43, v220, v43, vcc
	v_cmp_le_i32_e32 vcc, v2, v212
	v_add_u32_e32 v2, 18, v0
	s_nop 0
	v_cndmask_b32_e32 v27, v220, v27, vcc
	v_cmp_le_i32_e32 vcc, v2, v212
	v_add_u32_e32 v2, 50, v0
	s_nop 0
	v_cndmask_b32_e32 v44, v220, v44, vcc
	v_cmp_le_i32_e32 vcc, v2, v212
	v_add_u32_e32 v2, 19, v0
	s_nop 0
	v_cndmask_b32_e32 v28, v220, v28, vcc
	v_cmp_le_i32_e32 vcc, v2, v212
	v_add_u32_e32 v2, 51, v0
	s_nop 0
	v_cndmask_b32_e32 v45, v220, v45, vcc
	v_cmp_le_i32_e32 vcc, v2, v212
	v_add_u32_e32 v2, 24, v0
	s_nop 0
	v_cndmask_b32_e32 v29, v220, v29, vcc
	v_cmp_le_i32_e32 vcc, v2, v212
	v_add_u32_e32 v2, 56, v0
	s_nop 0
	v_cndmask_b32_e32 v46, v220, v46, vcc
	v_cmp_le_i32_e32 vcc, v2, v212
	v_add_u32_e32 v2, 25, v0
	s_nop 0
	v_cndmask_b32_e32 v30, v220, v30, vcc
	v_cmp_le_i32_e32 vcc, v2, v212
	v_add_u32_e32 v2, 57, v0
	s_nop 0
	v_cndmask_b32_e32 v47, v220, v47, vcc
	v_cmp_le_i32_e32 vcc, v2, v212
	v_add_u32_e32 v2, 26, v0
	s_nop 0
	v_cndmask_b32_e32 v31, v220, v31, vcc
	v_cmp_le_i32_e32 vcc, v2, v212
	v_add_u32_e32 v2, 58, v0
	s_nop 0
	v_cndmask_b32_e32 v48, v220, v48, vcc
	v_cmp_le_i32_e32 vcc, v2, v212
	v_add_u32_e32 v2, 27, v0
	v_add_u32_e32 v0, 59, v0
	v_cndmask_b32_e32 v32, v220, v32, vcc
	v_cmp_le_i32_e32 vcc, v2, v212
	s_nop 1
	v_cndmask_b32_e32 v49, v220, v49, vcc
	v_cmp_le_i32_e32 vcc, v0, v212
	s_nop 1
	v_cndmask_b32_e32 v33, v220, v33, vcc

; template <int DQK, int DV, bool MLA>
; __device__ __forceinline__ void attn_pass(LAS unsigned char* lds, const bf16_t* Qrow, const bf16_t* K0, int pitchK, const bf16_t* KrB, const bf16_t* Vt0, int NT, int q0w,
;                                           f32x16 (&o)[DV / 32], float& l_out, int tid) {
;     ...
;     bf16x8 q[ND];
; #pragma unroll
;     for (int d0 = 0; d0 < ND; ++d0) q[d0] = *(const GAS bf16x8*)(Qrow + 16 * d0 + 8 * hi);
; #pragma unroll
;     for (int d = 0; d < NDV; ++d)
; #pragma unroll
;         for (int r = 0; r < 16; ++r) o[d][r] = 0.f;
;     float m = 0.f, l = 0.f;
;     f32x16 negm;
; #pragma unroll
;     for (int r = 0; r < 16; ++r) negm[r] = 0.f;
; #pragma unroll
;     for (int d0 = 0; d0 < ND; ++d0) asm volatile("" : "+v"(q[d0]));
;     const bf16_t* ksrc; const bf16_t* rsrc = nullptr; const bf16_t* vsrc[NVC];
;     { const int row = 8 * wid + (lane >> 3), c = (lane & 7) ^ ((row >> 1) & 7); ksrc = K0 + (size_t)row * pitchK + c * 8; }
;     if (MLA) { const int row = 16 * (wid & 3) + (lane >> 2), c = (lane & 3) ^ ((row >> 2) & 3); rsrc = KrB + (size_t)row * 32 + c * 8; }
; #pragma unroll
;     for (int j = 0; j < NVC; ++j) { const int row = 8 * (wid + 8 * j) + (lane >> 3), c = (lane & 7) ^ ((row >> 1) & 7); vsrc[j] = Vt0 + (size_t)row * 64 + c * 8; }
;     ...
;     const int xs = (r32 >> 1) & 7;
;     const int yk = (xs ^ hi) << 4;
;     const int yr = (((r32 >> 2) & 3) ^ hi) << 4;
;     bf16x8 kf[2 * ND];
;     ...
;     ATT_DMA_K(0, 0); ATT_DMA_V(0, 0); ATT_DMA_K(1, 1); ATT_DMA_V(1, 1); ATT_DMA_K(2, 2);
;     asm volatile("s_waitcnt vmcnt(0)" ::: "memory");
; __device__ __forceinline__ void attention_phase(const KP& p, LAS unsigned char* lds, unsigned char* ws, int rep) {
;     ...
;                 const float ia = 1.0f / lA;
; #pragma unroll
;                 for (int d = 0; d < 4; ++d)
; #pragma unroll
;                     for (int g = 0; g < 4; ++g) {
;                         u32x2 wv; wv.x = cvtpk(oA[d][4 * g] * ia, oA[d][4 * g + 1] * ia); wv.y = cvtpk(oA[d][4 * g + 2] * ia, oA[d][4 * g + 3] * ia);
;                         *(GAS u32x2*)(yo + 32 * d + 8 * g + 4 * hi) = wv;
;                     }
;             }
;             f32x16 oB[4]; float lB;
;             attn_pass<64, 128, false>(lds, Qd + (rb + q0w + r32) * 512 + (2 * h + 1) * 64, Kd + rb * 512 + (2 * h + 1) * 64, 512, nullptr, Vt, NT, q0w, oB, lB, tid);
.LBB0_130:
	s_or_b64 exec, exec, s[6:7]
	v_mov_b32_e32 v0, v242
	s_nop 1
	v_permlane32_swap_b32_e32 v242, v0
	v_add_f32_e32 v0, v242, v0
	v_div_scale_f32 v36, s[6:7], v0, v0, 1.0
	v_rcp_f32_e32 v37, v36
	v_lshlrev_b64 v[34:35], 11, v[194:195]
	v_lshl_add_u64 v[34:35], s[82:83], 0, v[34:35]
	v_lshl_add_u64 v[34:35], v[34:35], 0, s[16:17]
	v_fma_f32 v38, -v36, v37, 1.0
	v_fmac_f32_e32 v37, v38, v37
	v_div_scale_f32 v38, vcc, 1.0, v0, 1.0
	v_mul_f32_e32 v39, v38, v37
	v_fma_f32 v40, -v36, v39, v38
	v_fmac_f32_e32 v39, v40, v37
	v_fma_f32 v36, -v36, v39, v38
	v_div_fmas_f32 v36, v36, v37, v39
	v_div_fixup_f32 v36, v36, v0, 1.0
	v_lshlrev_b32_e32 v0, 3, v239
	v_lshl_add_u64 v[194:195], v[34:35], 0, v[0:1]
	v_pk_mul_f32 v[34:35], v[66:67], v[36:37] op_sel_hi:[1,0]
	v_pk_mul_f32 v[38:39], v[68:69], v[36:37] op_sel_hi:[1,0]
	v_cvt_pk_bf16_f32 v34, v34, v35
	v_cvt_pk_bf16_f32 v35, v38, v39
	s_waitcnt lgkmcnt(0)
	s_barrier
	global_store_dwordx2 v[194:195], v[34:35], off offset:1024
	v_pk_mul_f32 v[34:35], v[70:71], v[36:37] op_sel_hi:[1,0]
	v_pk_mul_f32 v[38:39], v[72:73], v[36:37] op_sel_hi:[1,0]
	v_cvt_pk_bf16_f32 v34, v34, v35
	v_cvt_pk_bf16_f32 v35, v38, v39
	global_store_dwordx2 v[194:195], v[34:35], off offset:1040
	v_pk_mul_f32 v[34:35], v[74:75], v[36:37] op_sel_hi:[1,0]
	v_pk_mul_f32 v[38:39], v[76:77], v[36:37] op_sel_hi:[1,0]
	v_cvt_pk_bf16_f32 v34, v34, v35
	v_cvt_pk_bf16_f32 v35, v38, v39
	global_store_dwordx2 v[194:195], v[34:35], off offset:1056
	v_pk_mul_f32 v[34:35], v[78:79], v[36:37] op_sel_hi:[1,0]
	v_pk_mul_f32 v[38:39], v[80:81], v[36:37] op_sel_hi:[1,0]
	v_cvt_pk_bf16_f32 v34, v34, v35
	v_cvt_pk_bf16_f32 v35, v38, v39
	global_store_dwordx2 v[194:195], v[34:35], off offset:1072
	v_pk_mul_f32 v[34:35], v[50:51], v[36:37] op_sel_hi:[1,0]
	v_pk_mul_f32 v[38:39], v[52:53], v[36:37] op_sel_hi:[1,0]
	v_pk_mul_f32 v[18:19], v[18:19], v[36:37] op_sel_hi:[1,0]
	v_pk_mul_f32 v[20:21], v[20:21], v[36:37] op_sel_hi:[1,0]
	v_pk_mul_f32 v[2:3], v[2:3], v[36:37] op_sel_hi:[1,0]
	v_pk_mul_f32 v[4:5], v[4:5], v[36:37] op_sel_hi:[1,0]
	v_cvt_pk_bf16_f32 v34, v34, v35
	v_cvt_pk_bf16_f32 v35, v38, v39
	v_cvt_pk_bf16_f32 v18, v18, v19
	v_cvt_pk_bf16_f32 v19, v20, v21
	v_cvt_pk_bf16_f32 v2, v2, v3
	v_cvt_pk_bf16_f32 v3, v4, v5
	global_store_dwordx2 v[194:195], v[34:35], off offset:1088
	v_pk_mul_f32 v[34:35], v[54:55], v[36:37] op_sel_hi:[1,0]
	v_pk_mul_f32 v[38:39], v[56:57], v[36:37] op_sel_hi:[1,0]
	global_store_dwordx2 v[194:195], v[18:19], off offset:1152
	v_pk_mul_f32 v[18:19], v[22:23], v[36:37] op_sel_hi:[1,0]
	v_pk_mul_f32 v[20:21], v[24:25], v[36:37] op_sel_hi:[1,0]
	global_store_dwordx2 v[194:195], v[2:3], off offset:1216
	v_pk_mul_f32 v[2:3], v[6:7], v[36:37] op_sel_hi:[1,0]
	v_pk_mul_f32 v[4:5], v[8:9], v[36:37] op_sel_hi:[1,0]
	v_cvt_pk_bf16_f32 v34, v34, v35
	v_cvt_pk_bf16_f32 v35, v38, v39
	v_cvt_pk_bf16_f32 v18, v18, v19
	v_cvt_pk_bf16_f32 v19, v20, v21
	v_cvt_pk_bf16_f32 v2, v2, v3
	v_cvt_pk_bf16_f32 v3, v4, v5
	global_store_dwordx2 v[194:195], v[34:35], off offset:1104
	v_pk_mul_f32 v[34:35], v[58:59], v[36:37] op_sel_hi:[1,0]
	v_pk_mul_f32 v[38:39], v[60:61], v[36:37] op_sel_hi:[1,0]
	global_store_dwordx2 v[194:195], v[18:19], off offset:1168
	v_pk_mul_f32 v[18:19], v[26:27], v[36:37] op_sel_hi:[1,0]
	v_pk_mul_f32 v[20:21], v[28:29], v[36:37] op_sel_hi:[1,0]
	global_store_dwordx2 v[194:195], v[2:3], off offset:1232
	v_pk_mul_f32 v[2:3], v[10:11], v[36:37] op_sel_hi:[1,0]
	v_pk_mul_f32 v[4:5], v[12:13], v[36:37] op_sel_hi:[1,0]
	v_cvt_pk_bf16_f32 v34, v34, v35
	v_cvt_pk_bf16_f32 v35, v38, v39
	v_cvt_pk_bf16_f32 v18, v18, v19
	v_cvt_pk_bf16_f32 v19, v20, v21
	v_cvt_pk_bf16_f32 v2, v2, v3
	v_cvt_pk_bf16_f32 v3, v4, v5
	global_store_dwordx2 v[194:195], v[34:35], off offset:1120
	v_pk_mul_f32 v[34:35], v[62:63], v[36:37] op_sel_hi:[1,0]
	v_pk_mul_f32 v[38:39], v[64:65], v[36:37] op_sel_hi:[1,0]
	global_store_dwordx2 v[194:195], v[18:19], off offset:1184
	v_pk_mul_f32 v[18:19], v[30:31], v[36:37] op_sel_hi:[1,0]
	v_pk_mul_f32 v[20:21], v[32:33], v[36:37] op_sel_hi:[1,0]
	global_store_dwordx2 v[194:195], v[2:3], off offset:1248
	v_pk_mul_f32 v[2:3], v[14:15], v[36:37] op_sel_hi:[1,0]
	v_pk_mul_f32 v[4:5], v[16:17], v[36:37] op_sel_hi:[1,0]
	v_cvt_pk_bf16_f32 v34, v34, v35
	v_cvt_pk_bf16_f32 v35, v38, v39
	v_cvt_pk_bf16_f32 v18, v18, v19
	v_cvt_pk_bf16_f32 v19, v20, v21
	v_cvt_pk_bf16_f32 v2, v2, v3
	v_cvt_pk_bf16_f32 v3, v4, v5
	global_store_dwordx2 v[194:195], v[34:35], off offset:1136
	global_store_dwordx2 v[194:195], v[18:19], off offset:1200
	global_store_dwordx2 v[194:195], v[2:3], off offset:1264
	global_load_dwordx4 v[114:117], v[196:197], off offset:128
	global_load_dwordx4 v[118:121], v[196:197], off offset:160
	global_load_dwordx4 v[122:125], v[196:197], off offset:192
	global_load_dwordx4 v[126:129], v[196:197], off offset:224
	v_readfirstlane_b32 s6, v240
	s_ashr_i32 s6, s6, 6
	s_lshl_b32 s16, s6, 10
	v_lshl_or_b32 v2, s6, 3, v241
	v_lshrrev_b32_e32 v0, 1, v2
	v_xor_b32_e32 v0, v0, v240
	v_ashrrev_i32_e32 v3, 31, v2
	v_lshlrev_b64 v[4:5], 10, v[2:3]
	v_lshlrev_b64 v[2:3], 7, v[2:3]
	v_lshlrev_b32_e32 v0, 4, v0
	v_lshl_add_u64 v[2:3], s[44:45], 0, v[2:3]
	v_and_b32_e32 v0, 0x70, v0
	v_lshl_add_u64 v[66:67], v[2:3], 0, v[0:1]
	v_lshl_add_u64 v[2:3], s[48:49], 0, v[4:5]
	v_lshl_add_u64 v[2:3], v[2:3], 0, v[0:1]
	v_lshl_add_u64 v[70:71], v[2:3], 0, s[34:35]
	s_add_i32 s16, s16, 0
	s_mov_b32 s6, m0
	s_mov_b32 m0, s16
	s_nop 0
	global_load_lds_dwordx4 v[70:71], off
	s_mov_b32 m0, s6
	s_add_i32 s52, s16, 0x8000
	s_mov_b32 s6, m0
	s_mov_b32 m0, s52
	s_nop 0
	global_load_lds_dwordx4 v[66:67], off
	s_mov_b32 m0, s6
	v_lshl_add_u64 v[68:69], v[66:67], 0, s[24:25]
	s_add_i32 s6, s16, 0xa000
	s_mov_b32 s7, m0
	s_mov_b32 m0, s6
	s_nop 0
	global_load_lds_dwordx4 v[68:69], off
	s_mov_b32 m0, s7
	s_mov_b64 s[6:7], 0x10080
	v_lshl_add_u64 v[4:5], v[2:3], 0, s[6:7]
	s_add_i32 s6, s16, 0x2000
	s_mov_b32 s7, m0
	s_mov_b32 m0, s6
	s_nop 0
	global_load_lds_dwordx4 v[4:5], off
	s_mov_b32 m0, s7
	v_lshl_add_u64 v[4:5], v[66:67], 0, s[18:19]
	s_add_i32 s6, s16, 0xc000
	s_mov_b32 s7, m0
	s_mov_b32 m0, s6
	s_nop 0
	global_load_lds_dwordx4 v[4:5], off
	s_mov_b32 m0, s7
	v_lshl_add_u64 v[4:5], v[66:67], 0, s[30:31]
	s_add_i32 s6, s16, 0xe000
	s_mov_b32 s7, m0
	s_mov_b32 m0, s6
	s_nop 0
	global_load_lds_dwordx4 v[4:5], off
	s_mov_b32 m0, s7
	s_mov_b64 s[6:7], 0x20080
	v_lshl_add_u64 v[2:3], v[2:3], 0, s[6:7]
	s_add_i32 s6, s16, 0x4000
	s_mov_b32 s7, m0
	s_mov_b32 m0, s6
	s_nop 0
	global_load_lds_dwordx4 v[2:3], off
	s_mov_b32 m0, s7
	s_waitcnt vmcnt(0)
	s_barrier
; #define LAS __attribute__((address_space(3)))
; #define MFMA32(a, b, c) __builtin_amdgcn_mfma_f32_32x32x16_bf16((a), (b), (c), 0, 0, 0)
; #define PV_IDX(g) (((g) & 1) * 4 + PV_KS(g))
; template <int DQK, int DV, bool MLA>
; __device__ __forceinline__ void attn_pass(LAS unsigned char* lds, const bf16_t* Qrow, const bf16_t* K0, int pitchK, const bf16_t* KrB, const bf16_t* Vt0, int NT, int q0w,
;                                           f32x16 (&o)[DV / 32], float& l_out, int tid) {
;     ...
;     ATT_DMA_K(0, 0); ATT_DMA_V(0, 0); ATT_DMA_K(1, 1); ATT_DMA_V(1, 1); ATT_DMA_K(2, 2);
;     asm volatile("s_waitcnt vmcnt(0)" ::: "memory");
;     __builtin_amdgcn_s_barrier();
;     asm volatile("" ::: "memory");
;     ATT_KLOAD(0);
;     bf16x8 pf[4];
;     bool pend = false;
;     int vs_prev = 0;
;     ...
;     for (int t = 0; t < NT; ++t) {
;         const bool far = t + 3 < NT;
;         if (far) ATT_DMA_K(t + 3, (t + 3) & 3);
;         if (t + 2 < NT) ATT_DMA_V(t + 2, (t + 2) & 3);
;         const LAS unsigned char* vp = lds + VOFF + vs_prev * VB + r32 * 128;
;         if (64 * t <= q0w + 31) {
;             f32x16 s0, s1;
;             if constexpr (MLA) { s0 = negm; s1 = negm; }
;             else {
; #pragma unroll
;                 for (int r = 0; r < 16; ++r) { s0[r] = 0.f; s1[r] = 0.f; }
;             }
;             __builtin_amdgcn_s_setprio(1);
; #pragma unroll
;             for (int d0 = 0; d0 < ND; ++d0) { s0 = MFMA32(kf[2 * d0], q[d0], s0); s1 = MFMA32(kf[2 * d0 + 1], q[d0], s1); }
;             __builtin_amdgcn_s_setprio(0);
;             __builtin_amdgcn_sched_barrier(0);
;             if (t + 1 < NT) ATT_KLOAD((t + 1) & 3);
;             bf16x8 vf[8];
;             if (pend) {
; #pragma unroll
;                 for (int g = 0; g < 8; ++g) vf[PV_IDX(g)] = VFRAG(vp, PV_D(g), PV_KS(g));
;             }
;             __builtin_amdgcn_sched_barrier(0);
;             if (64 * t + 63 > q0w) {
;                 int hi_l = hi; asm volatile("" : "+v"(hi_l));
;                 const int qrow = q0w + r32, kb0 = 64 * t + 4 * hi_l;
; #pragma unroll
;                 for (int r = 0; r < 16; ++r) { const int kv = kb0 + (r & 3) + 8 * (r >> 2); if (kv > qrow) s0[r] = -INFINITY; if (kv + 32 > qrow) s1[r] = -INFINITY; }
;             }
	s_andn2_b64 vcc, exec, s[46:47]
	s_cbranch_vccnz .LBB0_168
	s_waitcnt lgkmcnt(0)
	ds_read_b128 v[130:133], v213 offset:4096
	ds_read_b128 v[134:137], v213
	ds_read_b128 v[138:141], v214 offset:4096
	ds_read_b128 v[142:145], v214
	ds_read_b128 v[146:149], v215 offset:4096
	ds_read_b128 v[150:153], v215
	ds_read_b128 v[154:157], v243 offset:4096
	ds_read_b128 v[158:161], v243
	v_lshl_add_u64 v[2:3], v[70:71], 0, s[26:27]
	s_add_i32 s6, s16, 0x6000
	s_mov_b32 s7, m0
	s_mov_b32 m0, s6
	s_nop 0
	global_load_lds_dwordx4 v[2:3], off
	s_mov_b32 m0, s7
	v_lshl_add_u64 v[2:3], v[68:69], 0, s[22:23]
	v_lshl_add_u64 v[4:5], v[66:67], 0, s[22:23]
	s_add_i32 s6, s16, 0x10000
	s_mov_b32 s7, m0
	s_mov_b32 m0, s6
	s_nop 0
	global_load_lds_dwordx4 v[4:5], off
	s_mov_b32 m0, s7
	s_add_i32 s6, s16, 0x12000
	s_mov_b32 s7, m0
	s_mov_b32 m0, s6
	s_nop 0
	global_load_lds_dwordx4 v[2:3], off
	s_mov_b32 m0, s7
	v_mov_b32_e32 v2, v1
	v_mov_b32_e32 v3, v1
	v_mov_b32_e32 v4, v1
	v_mov_b32_e32 v5, v1
	v_mov_b32_e32 v6, v1
	v_mov_b32_e32 v7, v1
	v_mov_b32_e32 v8, v1
	v_mov_b32_e32 v9, v1
	v_mov_b32_e32 v10, v1
	v_mov_b32_e32 v11, v1
	v_mov_b32_e32 v12, v1
	v_mov_b32_e32 v13, v1
	v_mov_b32_e32 v14, v1
	v_mov_b32_e32 v15, v1
	v_mov_b32_e32 v0, v1
	v_mov_b64_e32 v[16:17], v[14:15]
	v_cmp_lt_i32_e64 s[48:49], -1, v202
	v_mov_b32_e32 v207, 0
	v_mov_b32_e32 v206, 0
	v_mov_b64_e32 v[14:15], v[12:13]
	v_mov_b64_e32 v[12:13], v[10:11]
	v_mov_b64_e32 v[10:11], v[8:9]
	v_mov_b64_e32 v[8:9], v[6:7]
	v_mov_b64_e32 v[6:7], v[4:5]
	v_mov_b64_e32 v[4:5], v[2:3]
	v_mov_b64_e32 v[2:3], v[0:1]
	s_and_saveexec_b64 s[44:45], s[48:49]
	s_cbranch_execz .LBB0_135
	s_setprio 1
	s_waitcnt lgkmcnt(0)
	v_mfma_f32_32x32x16_bf16 v[34:49], v[158:161], v[114:117], 0
	v_mfma_f32_32x32x16_bf16 v[18:33], v[154:157], v[114:117], 0
	v_mfma_f32_32x32x16_bf16 v[34:49], v[150:153], v[118:121], v[34:49]
	v_mfma_f32_32x32x16_bf16 v[18:33], v[146:149], v[118:121], v[18:33]
	v_mfma_f32_32x32x16_bf16 v[34:49], v[142:145], v[122:125], v[34:49]
	v_mfma_f32_32x32x16_bf16 v[18:33], v[138:141], v[122:125], v[18:33]
	v_mfma_f32_32x32x16_bf16 v[34:49], v[134:137], v[126:129], v[34:49]
	v_mfma_f32_32x32x16_bf16 v[18:33], v[130:133], v[126:129], v[18:33]
	s_setprio 0
	ds_read_b128 v[158:161], v243 offset:8192
	ds_read_b128 v[154:157], v243 offset:12288
	ds_read_b128 v[150:153], v215 offset:8192
	ds_read_b128 v[146:149], v215 offset:12288
	ds_read_b128 v[142:145], v214 offset:8192
	ds_read_b128 v[138:141], v214 offset:12288
	ds_read_b128 v[134:137], v213 offset:8192
	ds_read_b128 v[130:133], v213 offset:12288
	v_cmp_gt_u32_e32 vcc, 63, v202
	s_and_saveexec_b64 s[6:7], vcc
	s_cbranch_execz .LBB0_134
	v_mov_b32_e32 v0, v239
	s_nop 0
	v_lshlrev_b32_e32 v0, 2, v0
	v_add_u32_e32 v2, 32, v0
	v_cmp_le_i32_e32 vcc, v2, v212
	v_add_u32_e32 v2, 33, v0
	s_nop 0
	v_cndmask_b32_e32 v18, v220, v18, vcc
	v_cmp_lt_i32_e32 vcc, v0, v212
	s_nop 1
	v_cndmask_b32_e32 v35, v220, v35, vcc
	v_cmp_le_i32_e32 vcc, v0, v212
	s_nop 1
	v_cndmask_b32_e32 v34, v220, v34, vcc
	v_cmp_le_i32_e32 vcc, v2, v212
	v_or_b32_e32 v2, 2, v0
	s_nop 0
	v_cndmask_b32_e32 v19, v220, v19, vcc
	v_cmp_le_i32_e32 vcc, v2, v212
	v_add_u32_e32 v2, 34, v0
	s_nop 0
	v_cndmask_b32_e32 v36, v220, v36, vcc
	v_cmp_le_i32_e32 vcc, v2, v212
	v_or_b32_e32 v2, 3, v0
	s_nop 0
	v_cndmask_b32_e32 v20, v220, v20, vcc
	v_cmp_le_i32_e32 vcc, v2, v212
	v_add_u32_e32 v2, 35, v0
	s_nop 0
	v_cndmask_b32_e32 v37, v220, v37, vcc
	v_cmp_le_i32_e32 vcc, v2, v212
	v_add_u32_e32 v2, 8, v0
	s_nop 0
	v_cndmask_b32_e32 v21, v220, v21, vcc
	v_cmp_le_i32_e32 vcc, v2, v212
	v_add_u32_e32 v2, 40, v0
	s_nop 0
	v_cndmask_b32_e32 v38, v220, v38, vcc
	v_cmp_le_i32_e32 vcc, v2, v212
	v_add_u32_e32 v2, 9, v0
	s_nop 0
	v_cndmask_b32_e32 v22, v220, v22, vcc
	v_cmp_le_i32_e32 vcc, v2, v212
	v_add_u32_e32 v2, 41, v0
	s_nop 0
	v_cndmask_b32_e32 v39, v220, v39, vcc
	v_cmp_le_i32_e32 vcc, v2, v212
	v_add_u32_e32 v2, 10, v0
	s_nop 0
	v_cndmask_b32_e32 v23, v220, v23, vcc
	v_cmp_le_i32_e32 vcc, v2, v212
	v_add_u32_e32 v2, 42, v0
	s_nop 0
	v_cndmask_b32_e32 v40, v220, v40, vcc
	v_cmp_le_i32_e32 vcc, v2, v212
	v_add_u32_e32 v2, 11, v0
	s_nop 0
	v_cndmask_b32_e32 v24, v220, v24, vcc
	v_cmp_le_i32_e32 vcc, v2, v212
	v_add_u32_e32 v2, 43, v0
	s_nop 0
	v_cndmask_b32_e32 v41, v220, v41, vcc
	v_cmp_le_i32_e32 vcc, v2, v212
	v_add_u32_e32 v2, 16, v0
	s_nop 0
	v_cndmask_b32_e32 v25, v220, v25, vcc
	v_cmp_le_i32_e32 vcc, v2, v212
	v_add_u32_e32 v2, 48, v0
	s_nop 0
	v_cndmask_b32_e32 v42, v220, v42, vcc
	v_cmp_le_i32_e32 vcc, v2, v212
	v_add_u32_e32 v2, 17, v0
	s_nop 0
	v_cndmask_b32_e32 v26, v220, v26, vcc
	v_cmp_le_i32_e32 vcc, v2, v212
	v_add_u32_e32 v2, 49, v0
	s_nop 0
	v_cndmask_b32_e32 v43, v220, v43, vcc
	v_cmp_le_i32_e32 vcc, v2, v212
	v_add_u32_e32 v2, 18, v0
	s_nop 0
	v_cndmask_b32_e32 v27, v220, v27, vcc
	v_cmp_le_i32_e32 vcc, v2, v212
	v_add_u32_e32 v2, 50, v0
	s_nop 0
	v_cndmask_b32_e32 v44, v220, v44, vcc
	v_cmp_le_i32_e32 vcc, v2, v212
	v_add_u32_e32 v2, 19, v0
	s_nop 0
	v_cndmask_b32_e32 v28, v220, v28, vcc
	v_cmp_le_i32_e32 vcc, v2, v212
	v_add_u32_e32 v2, 51, v0
	s_nop 0
	v_cndmask_b32_e32 v45, v220, v45, vcc
	v_cmp_le_i32_e32 vcc, v2, v212
	v_add_u32_e32 v2, 24, v0
	s_nop 0
	v_cndmask_b32_e32 v29, v220, v29, vcc
	v_cmp_le_i32_e32 vcc, v2, v212
	v_add_u32_e32 v2, 56, v0
	s_nop 0
	v_cndmask_b32_e32 v46, v220, v46, vcc
	v_cmp_le_i32_e32 vcc, v2, v212
	v_add_u32_e32 v2, 25, v0
	s_nop 0
	v_cndmask_b32_e32 v30, v220, v30, vcc
	v_cmp_le_i32_e32 vcc, v2, v212
	v_add_u32_e32 v2, 57, v0
	s_nop 0
	v_cndmask_b32_e32 v47, v220, v47, vcc
	v_cmp_le_i32_e32 vcc, v2, v212
	v_add_u32_e32 v2, 26, v0
	s_nop 0
	v_cndmask_b32_e32 v31, v220, v31, vcc
	v_cmp_le_i32_e32 vcc, v2, v212
	v_add_u32_e32 v2, 58, v0
	s_nop 0
	v_cndmask_b32_e32 v48, v220, v48, vcc
	v_cmp_le_i32_e32 vcc, v2, v212
	v_add_u32_e32 v2, 27, v0
	v_add_u32_e32 v0, 59, v0
	v_cndmask_b32_e32 v32, v220, v32, vcc
	v_cmp_le_i32_e32 vcc, v2, v212
	s_nop 1
	v_cndmask_b32_e32 v49, v220, v49, vcc
	v_cmp_le_i32_e32 vcc, v0, v212
	s_nop 1
	v_cndmask_b32_e32 v33, v220, v33, vcc
